# variant of v32: the 8 exps issued right after each tile barrier are computed one tile earlier in PV group-1 MFMA gaps (renamed to free registers, consumers renamed)
# speedup vs baseline: 1.0001x; 1.0001x over previous
; #define SBAR() __builtin_amdgcn_sched_barrier(0)
; __device__ __forceinline__ void finishSM(f32x16& p0, f32x16& p1, float alpha, float& l_reg, bf16x8& pa0, bf16x8& pa1, bf16x8& pa2, bf16x8& pa3) {
;   for (int r = 0; r < 16; ++r) p1[r] = __builtin_amdgcn_exp2f(p1[r]);
;   float ps = 0; for (int r = 0; r < 16; ++r) ps += p0[r]; for (int r = 0; r < 16; ++r) ps += p1[r];
;   { auto rr = __builtin_amdgcn_permlane32_swap(__float_as_uint(ps), __float_as_uint(ps), false, false);
;     ps = __uint_as_float(rr[0]) + __uint_as_float(rr[1]); }
;   l_reg = l_reg * alpha + ps;
;     ...
;   PK4(p0, 0, pa0); PK4(p0, 8, pa1); PK4(p1, 0, pa2); PK4(p1, 8, pa3);
;     ...
; }
; template <int BOFF> __device__ __forceinline__ void qkt_i(f32x16& p0, f32x16& p1, const int (&kb)[4], const bf16x8* qr) {
;   p0 = f32x16{}; p1 = f32x16{};
; #pragma unroll
;   for (int d0 = 0; d0 < 8; ++d0) { const int off = BOFF + (d0 >> 2) * 128;
;     const bf16x8 b0 = LDSV(kb[d0 & 3] + off), b1 = LDSV(kb[d0 & 3] + off + 8192);
;     p0 = __builtin_amdgcn_mfma_f32_32x32x16_bf16(b0, qr[d0], p0, 0, 0, 0);
;     p1 = __builtin_amdgcn_mfma_f32_32x32x16_bf16(b1, qr[d0], p1, 0, 0, 0); }
; }
; template <int D0, int BOFF> __device__ __forceinline__ void pv_one_i(f32x16& od, int vb, bf16x8 pa0, bf16x8 pa1, bf16x8 pa2, bf16x8 pa3) {
;   const s16x4 l0 = tr_read<BOFF + v_rd_off(D0, 0, 0)>(vb), h0 = tr_read<BOFF + v_rd_off(D0, 0, 1)>(vb), l1 = tr_read<BOFF + v_rd_off(D0, 1, 0)>(vb), h1 = tr_read<BOFF + v_rd_off(D0, 1, 1)>(vb);
;   const s16x4 l2 = tr_read<BOFF + v_rd_off(D0, 2, 0)>(vb), h2 = tr_read<BOFF + v_rd_off(D0, 2, 1)>(vb), l3 = tr_read<BOFF + v_rd_off(D0, 3, 0)>(vb), h3 = tr_read<BOFF + v_rd_off(D0, 3, 1)>(vb);
;   asm volatile("s_waitcnt lgkmcnt(0)" ::: "memory"); SBAR();
;     ...
;   od = __builtin_amdgcn_mfma_f32_32x32x16_bf16(pa0, PK(l0, h0), od, 0, 0, 0);
;   od = __builtin_amdgcn_mfma_f32_32x32x16_bf16(pa1, PK(l1, h1), od, 0, 0, 0);
;   od = __builtin_amdgcn_mfma_f32_32x32x16_bf16(pa2, PK(l2, h2), od, 0, 0, 0);
;   od = __builtin_amdgcn_mfma_f32_32x32x16_bf16(pa3, PK(l3, h3), od, 0, 0, 0);
;     ...
; }
; template <int BOFF> __device__ __forceinline__ void pv_i(f32x16* o, int vb, bf16x8 pa0, bf16x8 pa1, bf16x8 pa2, bf16x8 pa3) {
;   pv_one_i<0, BOFF>(o[0], vb, pa0, pa1, pa2, pa3); pv_one_i<1, BOFF>(o[1], vb, pa0, pa1, pa2, pa3); pv_one_i<2, BOFF>(o[2], vb, pa0, pa1, pa2, pa3); pv_one_i<3, BOFF>(o[3], vb, pa0, pa1, pa2, pa3);
; }
.LBB0_352:
	s_waitcnt lgkmcnt(0)
	s_barrier
	ds_read_b128 v[80:83], v207 offset:16384
	ds_read_b128 v[84:87], v207 offset:24576
	ds_read_b128 v[162:165], v208 offset:16384
	ds_read_b128 v[166:169], v208 offset:24576
	v_exp_f32_e32 v170, v72
	v_exp_f32_e32 v171, v73
	v_exp_f32_e32 v172, v74
	v_exp_f32_e32 v173, v75
	v_exp_f32_e32 v174, v76
	v_exp_f32_e32 v175, v77
	v_exp_f32_e32 v176, v78
	v_exp_f32_e32 v79, v79
	s_waitcnt lgkmcnt(3)
	v_mfma_f32_32x32x16_bf16 v[96:111], v[80:83], v[142:145], 0
	v_exp_f32_e32 v236, v64
	v_add_f32_e32 v64, 0, v229
	v_add_f32_e32 v64, v243, v64
	v_add_f32_e32 v64, v244, v64
	s_waitcnt lgkmcnt(2)
	v_mfma_f32_32x32x16_bf16 v[80:95], v[84:87], v[142:145], 0
	v_add_f32_e32 v64, v246, v64
	v_add_f32_e32 v64, v242, v64
	v_add_f32_e32 v64, v245, v64
	s_waitcnt lgkmcnt(1)
	v_mfma_f32_32x32x16_bf16 v[96:111], v[162:165], v[138:141], v[96:111]
	v_add_f32_e32 v64, v227, v64
	v_add_f32_e32 v64, v228, v64
	v_add_f32_e32 v64, v223, v64
	s_waitcnt lgkmcnt(0)
	v_mfma_f32_32x32x16_bf16 v[80:95], v[166:169], v[138:141], v[80:95]
	ds_read_b128 v[162:165], v209 offset:16384
	ds_read_b128 v[166:169], v209 offset:24576
	v_add_f32_e32 v64, v226, v64
	v_add_f32_e32 v64, v224, v64
	v_add_f32_e32 v64, v225, v64
	v_add_f32_e32 v64, v220, v64
	v_exp_f32_e32 v237, v65
	s_waitcnt lgkmcnt(1)
	v_mfma_f32_32x32x16_bf16 v[96:111], v[162:165], v[112:115], v[96:111]
	v_add_f32_e32 v64, v222, v64
	v_exp_f32_e32 v238, v66
	v_add_f32_e32 v64, v219, v64
	v_exp_f32_e32 v239, v67
	s_waitcnt lgkmcnt(0)
	v_mfma_f32_32x32x16_bf16 v[80:95], v[166:169], v[112:115], v[80:95]
	ds_read_b128 v[162:165], v210 offset:16384
	ds_read_b128 v[166:169], v210 offset:24576
	v_add_f32_e32 v64, v221, v64
	v_exp_f32_e32 v247, v68
	v_add_f32_e32 v64, v236, v64
	v_exp_f32_e32 v248, v69
	s_waitcnt lgkmcnt(1)
	v_mfma_f32_32x32x16_bf16 v[96:111], v[162:165], v[116:119], v[96:111]
	v_add_f32_e32 v64, v237, v64
	v_exp_f32_e32 v249, v70
	v_add_f32_e32 v64, v238, v64
	v_exp_f32_e32 v252, v71
	s_waitcnt lgkmcnt(0)
	v_mfma_f32_32x32x16_bf16 v[80:95], v[166:169], v[116:119], v[80:95]
	ds_read_b128 v[162:165], v190 offset:16384
	ds_read_b128 v[166:169], v190 offset:24576
	v_add_f32_e32 v64, v239, v64
	v_add_f32_e32 v64, v247, v64
	v_add_f32_e32 v64, v248, v64
	v_add_f32_e32 v64, v249, v64
	v_add_f32_e32 v64, v252, v64
	v_add_f32_e32 v64, v170, v64
	s_waitcnt lgkmcnt(1)
	v_mfma_f32_32x32x16_bf16 v[96:111], v[162:165], v[120:123], v[96:111]
	v_add_f32_e32 v64, v171, v64
	v_add_f32_e32 v64, v172, v64
	v_add_f32_e32 v64, v173, v64
	v_add_f32_e32 v64, v174, v64
	v_add_f32_e32 v64, v175, v64
	s_waitcnt lgkmcnt(0)
	v_mfma_f32_32x32x16_bf16 v[80:95], v[166:169], v[120:123], v[80:95]
	ds_read_b128 v[162:165], v191 offset:16384
	ds_read_b128 v[166:169], v191 offset:24576
	v_add_f32_e32 v64, v176, v64
	v_add_f32_e32 v64, v79, v64
	v_mov_b32_e32 v65, v64
	s_nop 1
	v_permlane32_swap_b32_e32 v64, v65
	v_add_f32_e32 v64, v64, v65
	s_waitcnt lgkmcnt(1)
	v_mfma_f32_32x32x16_bf16 v[96:111], v[162:165], v[124:127], v[96:111]
	v_add_f32_e32 v128, v215, v64
	v_cvt_pk_bf16_f32 v64, v229, v243
	v_cvt_pk_bf16_f32 v65, v244, v246
	v_cvt_pk_bf16_f32 v66, v242, v245
	v_cvt_pk_bf16_f32 v67, v227, v228
	s_waitcnt lgkmcnt(0)
	v_mfma_f32_32x32x16_bf16 v[80:95], v[166:169], v[124:127], v[80:95]
	ds_read_b128 v[162:165], v192 offset:16384
	ds_read_b128 v[166:169], v192 offset:24576
	v_cvt_pk_bf16_f32 v68, v223, v226
	v_cvt_pk_bf16_f32 v69, v224, v225
	v_cvt_pk_bf16_f32 v70, v220, v222
	v_cvt_pk_bf16_f32 v71, v219, v221
	v_cvt_pk_bf16_f32 v72, v236, v237
	v_cvt_pk_bf16_f32 v73, v238, v239
	s_waitcnt lgkmcnt(1)
	v_mfma_f32_32x32x16_bf16 v[96:111], v[162:165], v[130:133], v[96:111]
	v_cvt_pk_bf16_f32 v74, v247, v248
	v_cvt_pk_bf16_f32 v75, v249, v252
	v_cvt_pk_bf16_f32 v76, v170, v171
	v_cvt_pk_bf16_f32 v77, v172, v173
	v_cvt_pk_bf16_f32 v78, v174, v175
	s_waitcnt lgkmcnt(0)
	v_mfma_f32_32x32x16_bf16 v[80:95], v[166:169], v[130:133], v[80:95]
	ds_read_b128 v[162:165], v193 offset:16384
	ds_read_b128 v[166:169], v193 offset:24576
	ds_read_b64_tr_b16 v[180:181], v206 offset:0
	ds_read_b64_tr_b16 v[182:183], v206 offset:0x800
	ds_read_b64_tr_b16 v[184:185], v206 offset:0x1000
	ds_read_b64_tr_b16 v[186:187], v206 offset:0x1800
	ds_read_b64_tr_b16 v[216:217], v206 offset:0x2000
	ds_read_b64_tr_b16 v[218:219], v206 offset:0x2800
	ds_read_b64_tr_b16 v[220:221], v206 offset:0x3000
	ds_read_b64_tr_b16 v[222:223], v206 offset:0x3800
	v_cvt_pk_bf16_f32 v79, v176, v79
	s_nop 0
	v_permlane32_swap_b32_e32 v64, v66
	v_permlane32_swap_b32_e32 v65, v67
	v_permlane32_swap_b32_e32 v68, v70
	v_permlane32_swap_b32_e32 v69, v71
	s_waitcnt lgkmcnt(9)
	v_mfma_f32_32x32x16_bf16 v[96:111], v[162:165], v[134:137], v[96:111]
	v_permlane32_swap_b32_e32 v72, v74
	v_permlane32_swap_b32_e32 v73, v75
	v_permlane32_swap_b32_e32 v76, v78
	v_permlane32_swap_b32_e32 v77, v79
	s_waitcnt lgkmcnt(8)
	v_mfma_f32_32x32x16_bf16 v[80:95], v[166:169], v[134:137], v[80:95]
	s_waitcnt vmcnt(0)
	ds_write_b128 v211, v[146:149] offset:32768
	s_nop 0
	s_waitcnt lgkmcnt(7)
	v_mfma_f32_32x32x16_bf16 v[0:15], v[64:67], v[180:183], v[0:15]
	ds_read_b64_tr_b16 v[180:181], v206 offset:0x200
	ds_read_b64_tr_b16 v[182:183], v206 offset:0xa00
	v_add_co_u32_e32 v166, vcc, s19, v178
	s_nop 1
	v_addc_co_u32_e32 v167, vcc, -1, v179, vcc
	v_add_co_u32_e32 v170, vcc, s20, v178
	s_nop 1
	v_addc_co_u32_e32 v171, vcc, -1, v179, vcc
	s_waitcnt lgkmcnt(7)
	v_mfma_f32_32x32x16_bf16 v[0:15], v[68:71], v[184:187], v[0:15]
	ds_read_b64_tr_b16 v[184:185], v206 offset:0x1200
	ds_read_b64_tr_b16 v[186:187], v206 offset:0x1a00
	global_load_dwordx4 v[162:165], v[166:167], off
	s_nop 0
	global_load_dwordx4 v[166:169], v[166:167], off offset:-512
	s_nop 0
	global_load_dwordx4 v[174:177], v[170:171], off
	s_nop 0
	global_load_dwordx4 v[170:173], v[170:171], off offset:-512
	s_waitcnt lgkmcnt(7)
; #define SBAR() __builtin_amdgcn_sched_barrier(0)
; __device__ __forceinline__ void partialSM_fixed(f32x16& p0) {
;   for (int r = 0; r < 16; ++r) p0[r] = __builtin_amdgcn_exp2f(p0[r]);
; }
; __device__ __forceinline__ void finishSM(f32x16& p0, f32x16& p1, float alpha, float& l_reg, bf16x8& pa0, bf16x8& pa1, bf16x8& pa2, bf16x8& pa3) {
;   for (int r = 0; r < 16; ++r) p1[r] = __builtin_amdgcn_exp2f(p1[r]);
;   float ps = 0; for (int r = 0; r < 16; ++r) ps += p0[r]; for (int r = 0; r < 16; ++r) ps += p1[r];
;   { auto rr = __builtin_amdgcn_permlane32_swap(__float_as_uint(ps), __float_as_uint(ps), false, false);
;     ps = __uint_as_float(rr[0]) + __uint_as_float(rr[1]); }
;   l_reg = l_reg * alpha + ps;
;     ...
;   PK4(p0, 0, pa0); PK4(p0, 8, pa1); PK4(p1, 0, pa2); PK4(p1, 8, pa3);
;     ...
; }
; template <int D0, int BOFF> __device__ __forceinline__ void pv_one_i(f32x16& od, int vb, bf16x8 pa0, bf16x8 pa1, bf16x8 pa2, bf16x8 pa3) {
;   const s16x4 l0 = tr_read<BOFF + v_rd_off(D0, 0, 0)>(vb), h0 = tr_read<BOFF + v_rd_off(D0, 0, 1)>(vb), l1 = tr_read<BOFF + v_rd_off(D0, 1, 0)>(vb), h1 = tr_read<BOFF + v_rd_off(D0, 1, 1)>(vb);
;   const s16x4 l2 = tr_read<BOFF + v_rd_off(D0, 2, 0)>(vb), h2 = tr_read<BOFF + v_rd_off(D0, 2, 1)>(vb), l3 = tr_read<BOFF + v_rd_off(D0, 3, 0)>(vb), h3 = tr_read<BOFF + v_rd_off(D0, 3, 1)>(vb);
;   asm volatile("s_waitcnt lgkmcnt(0)" ::: "memory"); SBAR();
;     ...
;   od = __builtin_amdgcn_mfma_f32_32x32x16_bf16(pa0, PK(l0, h0), od, 0, 0, 0);
;   od = __builtin_amdgcn_mfma_f32_32x32x16_bf16(pa1, PK(l1, h1), od, 0, 0, 0);
;   od = __builtin_amdgcn_mfma_f32_32x32x16_bf16(pa2, PK(l2, h2), od, 0, 0, 0);
;   od = __builtin_amdgcn_mfma_f32_32x32x16_bf16(pa3, PK(l3, h3), od, 0, 0, 0);
;     ...
; }
; template <int BOFF> __device__ __forceinline__ void pv_i(f32x16* o, int vb, bf16x8 pa0, bf16x8 pa1, bf16x8 pa2, bf16x8 pa3) {
;   pv_one_i<0, BOFF>(o[0], vb, pa0, pa1, pa2, pa3); pv_one_i<1, BOFF>(o[1], vb, pa0, pa1, pa2, pa3); pv_one_i<2, BOFF>(o[2], vb, pa0, pa1, pa2, pa3); pv_one_i<3, BOFF>(o[3], vb, pa0, pa1, pa2, pa3);
; }
	v_mfma_f32_32x32x16_bf16 v[0:15], v[72:75], v[216:219], v[0:15]
	ds_read_b64_tr_b16 v[216:217], v206 offset:0x2200
	ds_read_b64_tr_b16 v[218:219], v206 offset:0x2a00
	s_waitcnt lgkmcnt(7)
	v_mfma_f32_32x32x16_bf16 v[0:15], v[76:79], v[220:223], v[0:15]
	ds_read_b64_tr_b16 v[220:221], v206 offset:0x3200
	ds_read_b64_tr_b16 v[222:223], v206 offset:0x3a00
	ds_write_b128 v212, v[150:153] offset:32768
	s_waitcnt lgkmcnt(7)
	v_mfma_f32_32x32x16_bf16 v[16:31], v[64:67], v[180:183], v[16:31]
	ds_read_b64_tr_b16 v[180:181], v206 offset:0x400
	ds_read_b64_tr_b16 v[182:183], v206 offset:0xc00
	v_exp_f32_e32 v200, v88
	v_exp_f32_e32 v201, v89
	s_waitcnt lgkmcnt(7)
	v_mfma_f32_32x32x16_bf16 v[16:31], v[68:71], v[184:187], v[16:31]
	ds_read_b64_tr_b16 v[184:185], v206 offset:0x1400
	ds_read_b64_tr_b16 v[186:187], v206 offset:0x1c00
	v_exp_f32_e32 v202, v90
	v_exp_f32_e32 v203, v91
	s_waitcnt lgkmcnt(7)
	v_mfma_f32_32x32x16_bf16 v[16:31], v[72:75], v[216:219], v[16:31]
	ds_read_b64_tr_b16 v[216:217], v206 offset:0x2400
	ds_read_b64_tr_b16 v[218:219], v206 offset:0x2c00
	v_exp_f32_e32 v204, v92
	v_exp_f32_e32 v205, v93
	s_waitcnt lgkmcnt(7)
	v_mfma_f32_32x32x16_bf16 v[16:31], v[76:79], v[220:223], v[16:31]
	ds_read_b64_tr_b16 v[220:221], v206 offset:0x3400
	ds_read_b64_tr_b16 v[222:223], v206 offset:0x3c00
	v_exp_f32_e32 v240, v94
	v_exp_f32_e32 v241, v95
	ds_write_b128 v213, v[154:157] offset:32768
	s_waitcnt lgkmcnt(7)
	v_mfma_f32_32x32x16_bf16 v[32:47], v[64:67], v[180:183], v[32:47]
	ds_read_b64_tr_b16 v[180:181], v206 offset:0x600
	ds_read_b64_tr_b16 v[182:183], v206 offset:0xe00
	v_exp_f32_e32 v215, v108
	v_exp_f32_e32 v188, v102
	s_waitcnt lgkmcnt(7)
	v_mfma_f32_32x32x16_bf16 v[32:47], v[68:71], v[184:187], v[32:47]
	ds_read_b64_tr_b16 v[184:185], v206 offset:0x1600
	ds_read_b64_tr_b16 v[186:187], v206 offset:0x1e00
	v_exp_f32_e32 v189, v103
	v_exp_f32_e32 v196, v104
	s_waitcnt lgkmcnt(7)
	v_mfma_f32_32x32x16_bf16 v[32:47], v[72:75], v[216:219], v[32:47]
	ds_read_b64_tr_b16 v[216:217], v206 offset:0x2600
	ds_read_b64_tr_b16 v[218:219], v206 offset:0x2e00
	v_exp_f32_e32 v197, v105
	v_exp_f32_e32 v198, v106
	s_waitcnt lgkmcnt(7)
	v_mfma_f32_32x32x16_bf16 v[32:47], v[76:79], v[220:223], v[32:47]
	ds_read_b64_tr_b16 v[220:221], v206 offset:0x3600
	ds_read_b64_tr_b16 v[222:223], v206 offset:0x3e00
	v_exp_f32_e32 v199, v107
	ds_write_b128 v214, v[158:161] offset:32768
	s_waitcnt lgkmcnt(7)
	v_mfma_f32_32x32x16_bf16 v[48:63], v[64:67], v[180:183], v[48:63]
	s_waitcnt vmcnt(4)
	v_exp_f32_e32 v181, v96
	v_exp_f32_e32 v183, v97
	s_waitcnt lgkmcnt(5)
	v_mfma_f32_32x32x16_bf16 v[48:63], v[68:71], v[184:187], v[48:63]
	v_exp_f32_e32 v184, v98
	v_exp_f32_e32 v185, v99
	v_exp_f32_e32 v186, v100
	v_exp_f32_e32 v187, v101
	s_waitcnt lgkmcnt(3)
	v_mfma_f32_32x32x16_bf16 v[48:63], v[72:75], v[216:219], v[48:63]
	v_exp_f32_e32 v216, v109
	v_exp_f32_e32 v217, v110
	v_exp_f32_e32 v218, v111
	s_waitcnt lgkmcnt(0)
	s_barrier
	v_mfma_f32_32x32x16_bf16 v[48:63], v[76:79], v[220:223], v[48:63]
	ds_read_b128 v[64:67], v207 offset:32768
	ds_read_b128 v[96:99], v207 offset:40960
	ds_read_b128 v[146:149], v208 offset:32768
	ds_read_b128 v[150:153], v208 offset:40960
	s_waitcnt lgkmcnt(3)
	v_mfma_f32_32x32x16_bf16 v[64:79], v[64:67], v[142:145], 0
	v_exp_f32_e32 v236, v80
	v_add_f32_e32 v80, 0, v181
	v_add_f32_e32 v80, v183, v80
	v_add_f32_e32 v80, v184, v80
	s_waitcnt lgkmcnt(2)
	v_mfma_f32_32x32x16_bf16 v[96:111], v[96:99], v[142:145], 0
	v_add_f32_e32 v80, v185, v80
	v_add_f32_e32 v80, v186, v80
	v_add_f32_e32 v80, v187, v80
	s_waitcnt lgkmcnt(1)
	v_mfma_f32_32x32x16_bf16 v[64:79], v[146:149], v[138:141], v[64:79]
	v_add_f32_e32 v80, v188, v80
	v_add_f32_e32 v80, v189, v80
	v_add_f32_e32 v80, v196, v80
	s_waitcnt lgkmcnt(0)
	v_mfma_f32_32x32x16_bf16 v[96:111], v[150:153], v[138:141], v[96:111]
	ds_read_b128 v[146:149], v209 offset:32768
	ds_read_b128 v[150:153], v209 offset:40960
	v_add_f32_e32 v80, v197, v80
	v_add_f32_e32 v80, v198, v80
	v_add_f32_e32 v80, v199, v80
	v_add_f32_e32 v80, v215, v80
	v_exp_f32_e32 v237, v81
	s_waitcnt lgkmcnt(1)
	v_mfma_f32_32x32x16_bf16 v[64:79], v[146:149], v[112:115], v[64:79]
	v_add_f32_e32 v80, v216, v80
	v_exp_f32_e32 v238, v82
	v_add_f32_e32 v80, v217, v80
	v_exp_f32_e32 v239, v83
	s_waitcnt lgkmcnt(0)
	v_mfma_f32_32x32x16_bf16 v[96:111], v[150:153], v[112:115], v[96:111]
	ds_read_b128 v[146:149], v210 offset:32768
	ds_read_b128 v[150:153], v210 offset:40960
	v_add_f32_e32 v80, v218, v80
	v_exp_f32_e32 v247, v84
	v_add_f32_e32 v80, v236, v80
	v_exp_f32_e32 v248, v85
	s_waitcnt lgkmcnt(1)
	v_mfma_f32_32x32x16_bf16 v[64:79], v[146:149], v[116:119], v[64:79]
	v_add_f32_e32 v80, v237, v80
	v_exp_f32_e32 v249, v86
	v_add_f32_e32 v80, v238, v80
	v_exp_f32_e32 v252, v87
	s_waitcnt lgkmcnt(0)
	v_mfma_f32_32x32x16_bf16 v[96:111], v[150:153], v[116:119], v[96:111]
	ds_read_b128 v[146:149], v190 offset:32768
	ds_read_b128 v[150:153], v190 offset:40960
	v_add_f32_e32 v80, v239, v80
	v_add_f32_e32 v80, v247, v80
	v_add_f32_e32 v80, v248, v80
	v_add_f32_e32 v80, v249, v80
	v_add_f32_e32 v80, v252, v80
	v_add_f32_e32 v80, v200, v80
	s_waitcnt lgkmcnt(1)
	v_mfma_f32_32x32x16_bf16 v[64:79], v[146:149], v[120:123], v[64:79]
	v_add_f32_e32 v80, v201, v80
	v_add_f32_e32 v80, v202, v80
	v_add_f32_e32 v80, v203, v80
	v_add_f32_e32 v80, v204, v80
	v_add_f32_e32 v80, v205, v80
	s_waitcnt lgkmcnt(0)
	v_mfma_f32_32x32x16_bf16 v[96:111], v[150:153], v[120:123], v[96:111]
	ds_read_b128 v[146:149], v191 offset:32768
	ds_read_b128 v[150:153], v191 offset:40960
	v_add_f32_e32 v80, v240, v80
	v_add_f32_e32 v180, v241, v80
	v_mov_b32_e32 v182, v180
	v_cvt_pk_bf16_f32 v80, v181, v183
	v_cvt_pk_bf16_f32 v81, v184, v185
	v_cvt_pk_bf16_f32 v82, v186, v187
	s_waitcnt lgkmcnt(1)
; #define SBAR() __builtin_amdgcn_sched_barrier(0)
; __device__ __forceinline__ void partialSM_fixed(f32x16& p0) {
;   for (int r = 0; r < 16; ++r) p0[r] = __builtin_amdgcn_exp2f(p0[r]);
; }
; __device__ __forceinline__ void finishSM(f32x16& p0, f32x16& p1, float alpha, float& l_reg, bf16x8& pa0, bf16x8& pa1, bf16x8& pa2, bf16x8& pa3) {
;   for (int r = 0; r < 16; ++r) p1[r] = __builtin_amdgcn_exp2f(p1[r]);
;   float ps = 0; for (int r = 0; r < 16; ++r) ps += p0[r]; for (int r = 0; r < 16; ++r) ps += p1[r];
;   { auto rr = __builtin_amdgcn_permlane32_swap(__float_as_uint(ps), __float_as_uint(ps), false, false);
;     ps = __uint_as_float(rr[0]) + __uint_as_float(rr[1]); }
;   l_reg = l_reg * alpha + ps;
;     ...
;   PK4(p0, 0, pa0); PK4(p0, 8, pa1); PK4(p1, 0, pa2); PK4(p1, 8, pa3);
;     ...
; }
; template <int D0, int BOFF> __device__ __forceinline__ void pv_one_i(f32x16& od, int vb, bf16x8 pa0, bf16x8 pa1, bf16x8 pa2, bf16x8 pa3) {
;   const s16x4 l0 = tr_read<BOFF + v_rd_off(D0, 0, 0)>(vb), h0 = tr_read<BOFF + v_rd_off(D0, 0, 1)>(vb), l1 = tr_read<BOFF + v_rd_off(D0, 1, 0)>(vb), h1 = tr_read<BOFF + v_rd_off(D0, 1, 1)>(vb);
;   const s16x4 l2 = tr_read<BOFF + v_rd_off(D0, 2, 0)>(vb), h2 = tr_read<BOFF + v_rd_off(D0, 2, 1)>(vb), l3 = tr_read<BOFF + v_rd_off(D0, 3, 0)>(vb), h3 = tr_read<BOFF + v_rd_off(D0, 3, 1)>(vb);
;   asm volatile("s_waitcnt lgkmcnt(0)" ::: "memory"); SBAR();
;     ...
;   od = __builtin_amdgcn_mfma_f32_32x32x16_bf16(pa0, PK(l0, h0), od, 0, 0, 0);
;   od = __builtin_amdgcn_mfma_f32_32x32x16_bf16(pa1, PK(l1, h1), od, 0, 0, 0);
;   od = __builtin_amdgcn_mfma_f32_32x32x16_bf16(pa2, PK(l2, h2), od, 0, 0, 0);
;   od = __builtin_amdgcn_mfma_f32_32x32x16_bf16(pa3, PK(l3, h3), od, 0, 0, 0);
;     ...
; }
; template <int BOFF> __device__ __forceinline__ void pv_i(f32x16* o, int vb, bf16x8 pa0, bf16x8 pa1, bf16x8 pa2, bf16x8 pa3) {
;   pv_one_i<0, BOFF>(o[0], vb, pa0, pa1, pa2, pa3); pv_one_i<1, BOFF>(o[1], vb, pa0, pa1, pa2, pa3); pv_one_i<2, BOFF>(o[2], vb, pa0, pa1, pa2, pa3); pv_one_i<3, BOFF>(o[3], vb, pa0, pa1, pa2, pa3);
; }
	v_mfma_f32_32x32x16_bf16 v[64:79], v[146:149], v[124:127], v[64:79]
	v_cvt_pk_bf16_f32 v83, v188, v189
	v_cvt_pk_bf16_f32 v84, v196, v197
	v_cvt_pk_bf16_f32 v85, v198, v199
	v_cvt_pk_bf16_f32 v86, v215, v216
	v_cvt_pk_bf16_f32 v87, v217, v218
	s_waitcnt lgkmcnt(0)
	v_mfma_f32_32x32x16_bf16 v[96:111], v[150:153], v[124:127], v[96:111]
	ds_read_b128 v[146:149], v192 offset:32768
	ds_read_b128 v[150:153], v192 offset:40960
	v_cvt_pk_bf16_f32 v88, v236, v237
	v_cvt_pk_bf16_f32 v89, v238, v239
	v_cvt_pk_bf16_f32 v90, v247, v248
	v_cvt_pk_bf16_f32 v91, v249, v252
	v_cvt_pk_bf16_f32 v92, v200, v201
	v_cvt_pk_bf16_f32 v93, v202, v203
	s_waitcnt lgkmcnt(1)
	v_mfma_f32_32x32x16_bf16 v[64:79], v[146:149], v[130:133], v[64:79]
	v_cvt_pk_bf16_f32 v94, v204, v205
	v_cvt_pk_bf16_f32 v95, v240, v241
	s_nop 1
	v_permlane32_swap_b32_e32 v180, v182
	v_permlane32_swap_b32_e32 v80, v82
	s_waitcnt lgkmcnt(0)
	v_mfma_f32_32x32x16_bf16 v[96:111], v[150:153], v[130:133], v[96:111]
	ds_read_b128 v[146:149], v193 offset:32768
	ds_read_b128 v[150:153], v193 offset:40960
	ds_read_b64_tr_b16 v[184:185], v206 offset:0x4000
	ds_read_b64_tr_b16 v[186:187], v206 offset:0x4800
	ds_read_b64_tr_b16 v[216:217], v206 offset:0x5000
	ds_read_b64_tr_b16 v[218:219], v206 offset:0x5800
	ds_read_b64_tr_b16 v[220:221], v206 offset:0x6000
	ds_read_b64_tr_b16 v[222:223], v206 offset:0x6800
	ds_read_b64_tr_b16 v[224:225], v206 offset:0x7000
	ds_read_b64_tr_b16 v[226:227], v206 offset:0x7800
	v_permlane32_swap_b32_e32 v81, v83
	v_permlane32_swap_b32_e32 v84, v86
	v_permlane32_swap_b32_e32 v85, v87
	v_permlane32_swap_b32_e32 v88, v90
	v_permlane32_swap_b32_e32 v89, v91
	v_permlane32_swap_b32_e32 v92, v94
	s_waitcnt lgkmcnt(9)
	v_mfma_f32_32x32x16_bf16 v[64:79], v[146:149], v[134:137], v[64:79]
	v_permlane32_swap_b32_e32 v93, v95
	s_waitcnt lgkmcnt(8)
	v_mfma_f32_32x32x16_bf16 v[96:111], v[150:153], v[134:137], v[96:111]
	s_waitcnt vmcnt(0)
	ds_write_b128 v211, v[162:165]
	s_nop 0
	s_waitcnt lgkmcnt(7)
	v_mfma_f32_32x32x16_bf16 v[0:15], v[80:83], v[184:187], v[0:15]
	ds_read_b64_tr_b16 v[184:185], v206 offset:0x4200
	ds_read_b64_tr_b16 v[186:187], v206 offset:0x4a00
	v_add_co_u32_e32 v150, vcc, s21, v178
	s_nop 1
	v_addc_co_u32_e32 v151, vcc, -1, v179, vcc
	v_add_co_u32_e32 v154, vcc, s22, v178
	s_nop 1
	v_addc_co_u32_e32 v155, vcc, -1, v179, vcc
	s_waitcnt lgkmcnt(7)
	v_mfma_f32_32x32x16_bf16 v[0:15], v[84:87], v[216:219], v[0:15]
	ds_read_b64_tr_b16 v[216:217], v206 offset:0x5200
	ds_read_b64_tr_b16 v[218:219], v206 offset:0x5a00
	global_load_dwordx4 v[146:149], v[150:151], off
	s_nop 0
	global_load_dwordx4 v[150:153], v[150:151], off offset:-512
	s_nop 0
	global_load_dwordx4 v[158:161], v[154:155], off
	s_nop 0
	global_load_dwordx4 v[154:157], v[154:155], off offset:-512
	s_waitcnt lgkmcnt(7)
	v_mfma_f32_32x32x16_bf16 v[0:15], v[88:91], v[220:223], v[0:15]
	ds_read_b64_tr_b16 v[220:221], v206 offset:0x6200
	ds_read_b64_tr_b16 v[222:223], v206 offset:0x6a00
	s_waitcnt lgkmcnt(7)
	v_mfma_f32_32x32x16_bf16 v[0:15], v[92:95], v[224:227], v[0:15]
	ds_read_b64_tr_b16 v[224:225], v206 offset:0x7200
	ds_read_b64_tr_b16 v[226:227], v206 offset:0x7a00
	ds_write_b128 v212, v[174:177]
	s_waitcnt lgkmcnt(7)
	v_mfma_f32_32x32x16_bf16 v[16:31], v[80:83], v[184:187], v[16:31]
	ds_read_b64_tr_b16 v[184:185], v206 offset:0x4400
	ds_read_b64_tr_b16 v[186:187], v206 offset:0x4c00
	v_exp_f32_e32 v200, v104
	v_exp_f32_e32 v201, v105
	s_waitcnt lgkmcnt(7)
	v_mfma_f32_32x32x16_bf16 v[16:31], v[84:87], v[216:219], v[16:31]
	ds_read_b64_tr_b16 v[216:217], v206 offset:0x5400
	ds_read_b64_tr_b16 v[218:219], v206 offset:0x5c00
	v_exp_f32_e32 v202, v106
	v_exp_f32_e32 v203, v107
	s_waitcnt lgkmcnt(7)
	v_mfma_f32_32x32x16_bf16 v[16:31], v[88:91], v[220:223], v[16:31]
	ds_read_b64_tr_b16 v[220:221], v206 offset:0x6400
	ds_read_b64_tr_b16 v[222:223], v206 offset:0x6c00
	v_exp_f32_e32 v204, v108
	v_exp_f32_e32 v205, v109
	s_waitcnt lgkmcnt(7)
	v_mfma_f32_32x32x16_bf16 v[16:31], v[92:95], v[224:227], v[16:31]
	ds_read_b64_tr_b16 v[224:225], v206 offset:0x7400
	ds_read_b64_tr_b16 v[226:227], v206 offset:0x7c00
	v_exp_f32_e32 v240, v110
	v_exp_f32_e32 v241, v111
	ds_write_b128 v213, v[166:169]
	s_waitcnt lgkmcnt(7)
	v_mfma_f32_32x32x16_bf16 v[32:47], v[80:83], v[184:187], v[32:47]
	ds_read_b64_tr_b16 v[184:185], v206 offset:0x4600
	ds_read_b64_tr_b16 v[186:187], v206 offset:0x4e00
	v_exp_f32_e32 v215, v74
	v_exp_f32_e32 v188, v68
	s_waitcnt lgkmcnt(7)
	v_mfma_f32_32x32x16_bf16 v[32:47], v[84:87], v[216:219], v[32:47]
	ds_read_b64_tr_b16 v[216:217], v206 offset:0x5600
	ds_read_b64_tr_b16 v[218:219], v206 offset:0x5e00
	v_exp_f32_e32 v189, v69
	v_exp_f32_e32 v196, v70
	s_waitcnt lgkmcnt(7)
	v_mfma_f32_32x32x16_bf16 v[32:47], v[88:91], v[220:223], v[32:47]
	ds_read_b64_tr_b16 v[220:221], v206 offset:0x6600
	ds_read_b64_tr_b16 v[222:223], v206 offset:0x6e00
	v_exp_f32_e32 v197, v71
	v_exp_f32_e32 v198, v72
	s_waitcnt lgkmcnt(7)
	v_mfma_f32_32x32x16_bf16 v[32:47], v[92:95], v[224:227], v[32:47]
	ds_read_b64_tr_b16 v[224:225], v206 offset:0x7600
	ds_read_b64_tr_b16 v[226:227], v206 offset:0x7e00
	v_exp_f32_e32 v199, v73
	ds_write_b128 v214, v[170:173]
	s_waitcnt lgkmcnt(7)
	v_mfma_f32_32x32x16_bf16 v[48:63], v[80:83], v[184:187], v[48:63]
	s_waitcnt vmcnt(4)
	v_exp_f32_e32 v184, v64
	v_exp_f32_e32 v185, v65
	v_exp_f32_e32 v186, v66
	v_exp_f32_e32 v187, v67
	s_waitcnt lgkmcnt(5)
	v_mfma_f32_32x32x16_bf16 v[48:63], v[84:87], v[216:219], v[48:63]
	v_exp_f32_e32 v219, v78
	v_exp_f32_e32 v216, v75
	s_waitcnt lgkmcnt(3)
	v_mfma_f32_32x32x16_bf16 v[48:63], v[88:91], v[220:223], v[48:63]
	v_exp_f32_e32 v220, v79
	v_exp_f32_e32 v217, v76
	v_exp_f32_e32 v218, v77
	s_waitcnt lgkmcnt(0)
	s_barrier
; __device__ __forceinline__ void finishSM(f32x16& p0, f32x16& p1, float alpha, float& l_reg, bf16x8& pa0, bf16x8& pa1, bf16x8& pa2, bf16x8& pa3) {
;   for (int r = 0; r < 16; ++r) p1[r] = __builtin_amdgcn_exp2f(p1[r]);
;   float ps = 0; for (int r = 0; r < 16; ++r) ps += p0[r]; for (int r = 0; r < 16; ++r) ps += p1[r];
;   { auto rr = __builtin_amdgcn_permlane32_swap(__float_as_uint(ps), __float_as_uint(ps), false, false);
;     ps = __uint_as_float(rr[0]) + __uint_as_float(rr[1]); }
;   l_reg = l_reg * alpha + ps;
;     ...
;   PK4(p0, 0, pa0); PK4(p0, 8, pa1); PK4(p1, 0, pa2); PK4(p1, 8, pa3);
;     ...
; }
	v_mfma_f32_32x32x16_bf16 v[48:63], v[92:95], v[224:227], v[48:63]
	ds_read_b128 v[64:67], v207
	ds_read_b128 v[68:71], v207 offset:8192
	ds_read_b128 v[162:165], v208
	ds_read_b128 v[166:169], v208 offset:8192
	s_waitcnt lgkmcnt(3)
	v_mfma_f32_32x32x16_bf16 v[80:95], v[64:67], v[142:145], 0
	v_exp_f32_e32 v236, v96
	v_add_f32_e32 v96, 0, v184
	v_add_f32_e32 v96, v185, v96
	v_add_f32_e32 v96, v186, v96
	s_waitcnt lgkmcnt(2)
	v_mfma_f32_32x32x16_bf16 v[64:79], v[68:71], v[142:145], 0
	v_add_f32_e32 v96, v187, v96
	v_add_f32_e32 v96, v188, v96
	v_add_f32_e32 v96, v189, v96
	s_waitcnt lgkmcnt(1)
	v_mfma_f32_32x32x16_bf16 v[80:95], v[162:165], v[138:141], v[80:95]
	v_add_f32_e32 v96, v196, v96
	v_add_f32_e32 v96, v197, v96
	v_add_f32_e32 v96, v198, v96
	s_waitcnt lgkmcnt(0)
	v_mfma_f32_32x32x16_bf16 v[64:79], v[166:169], v[138:141], v[64:79]
	ds_read_b128 v[162:165], v209
	ds_read_b128 v[166:169], v209 offset:8192
	v_add_f32_e32 v96, v199, v96
	v_add_f32_e32 v96, v215, v96
	v_add_f32_e32 v96, v216, v96
	v_add_f32_e32 v96, v217, v96
	v_exp_f32_e32 v237, v97
	s_waitcnt lgkmcnt(1)
	v_mfma_f32_32x32x16_bf16 v[80:95], v[162:165], v[112:115], v[80:95]
	v_add_f32_e32 v96, v218, v96
	v_exp_f32_e32 v238, v98
	v_add_f32_e32 v96, v219, v96
	v_exp_f32_e32 v239, v99
	s_waitcnt lgkmcnt(0)
	v_mfma_f32_32x32x16_bf16 v[64:79], v[166:169], v[112:115], v[64:79]
	ds_read_b128 v[162:165], v210
	ds_read_b128 v[166:169], v210 offset:8192
	v_add_f32_e32 v96, v220, v96
	v_exp_f32_e32 v247, v100
	v_add_f32_e32 v96, v236, v96
	v_exp_f32_e32 v248, v101
	s_waitcnt lgkmcnt(1)
	v_mfma_f32_32x32x16_bf16 v[80:95], v[162:165], v[116:119], v[80:95]
	v_add_f32_e32 v96, v237, v96
	v_exp_f32_e32 v249, v102
	v_add_f32_e32 v96, v238, v96
	v_exp_f32_e32 v252, v103
	s_waitcnt lgkmcnt(0)
	v_mfma_f32_32x32x16_bf16 v[64:79], v[166:169], v[116:119], v[64:79]
	ds_read_b128 v[162:165], v190 offset:0
	ds_read_b128 v[166:169], v190 offset:8192
	v_add_f32_e32 v96, v239, v96
	v_add_f32_e32 v96, v247, v96
	v_add_f32_e32 v96, v248, v96
	v_add_f32_e32 v96, v249, v96
	v_add_f32_e32 v96, v252, v96
	v_add_f32_e32 v96, v200, v96
	s_waitcnt lgkmcnt(1)
	v_mfma_f32_32x32x16_bf16 v[80:95], v[162:165], v[120:123], v[80:95]
	v_add_f32_e32 v96, v201, v96
	v_add_f32_e32 v96, v202, v96
	v_add_f32_e32 v96, v203, v96
	v_add_f32_e32 v96, v204, v96
	v_add_f32_e32 v96, v205, v96
	s_waitcnt lgkmcnt(0)
	v_mfma_f32_32x32x16_bf16 v[64:79], v[166:169], v[120:123], v[64:79]
	ds_read_b128 v[162:165], v191 offset:0
	ds_read_b128 v[166:169], v191 offset:8192
	v_add_f32_e32 v96, v240, v96
	v_add_f32_e32 v181, v241, v96
	v_mov_b32_e32 v183, v181
	s_nop 1
	v_permlane32_swap_b32_e32 v181, v183
	v_pk_add_f32 v[96:97], v[180:181], v[182:183]
	s_waitcnt lgkmcnt(1)
	v_mfma_f32_32x32x16_bf16 v[80:95], v[162:165], v[124:127], v[80:95]
	s_nop 0
	v_add_f32_e32 v96, v128, v96
	v_add_f32_e32 v128, v96, v97
	v_cvt_pk_bf16_f32 v96, v184, v185
	v_cvt_pk_bf16_f32 v97, v186, v187
	s_waitcnt lgkmcnt(0)
	v_mfma_f32_32x32x16_bf16 v[64:79], v[166:169], v[124:127], v[64:79]
	ds_read_b128 v[162:165], v192 offset:0
	ds_read_b128 v[166:169], v192 offset:8192
	v_cvt_pk_bf16_f32 v98, v188, v189
	v_cvt_pk_bf16_f32 v99, v196, v197
	v_cvt_pk_bf16_f32 v100, v198, v199
	v_cvt_pk_bf16_f32 v101, v215, v216
	v_cvt_pk_bf16_f32 v102, v217, v218
	v_cvt_pk_bf16_f32 v103, v219, v220
	s_waitcnt lgkmcnt(1)
	v_mfma_f32_32x32x16_bf16 v[80:95], v[162:165], v[130:133], v[80:95]
	v_cvt_pk_bf16_f32 v104, v236, v237
	v_cvt_pk_bf16_f32 v105, v238, v239
	v_cvt_pk_bf16_f32 v106, v247, v248
	v_cvt_pk_bf16_f32 v107, v249, v252
	v_cvt_pk_bf16_f32 v108, v200, v201
	s_waitcnt lgkmcnt(0)
	v_mfma_f32_32x32x16_bf16 v[64:79], v[166:169], v[130:133], v[64:79]
	ds_read_b128 v[162:165], v193 offset:0
	ds_read_b128 v[166:169], v193 offset:8192
	ds_read_b64_tr_b16 v[180:181], v206 offset:0x8000
	ds_read_b64_tr_b16 v[182:183], v206 offset:0x8800
	ds_read_b64_tr_b16 v[184:185], v206 offset:0x9000
	ds_read_b64_tr_b16 v[186:187], v206 offset:0x9800
	ds_read_b64_tr_b16 v[216:217], v206 offset:0xa000
	ds_read_b64_tr_b16 v[218:219], v206 offset:0xa800
	ds_read_b64_tr_b16 v[220:221], v206 offset:0xb000
	ds_read_b64_tr_b16 v[222:223], v206 offset:0xb800
	v_cvt_pk_bf16_f32 v109, v202, v203
	v_cvt_pk_bf16_f32 v110, v204, v205
	v_cvt_pk_bf16_f32 v111, v240, v241
	s_nop 0
	v_permlane32_swap_b32_e32 v96, v98
	v_permlane32_swap_b32_e32 v97, v99
	s_waitcnt lgkmcnt(9)
	v_mfma_f32_32x32x16_bf16 v[80:95], v[162:165], v[134:137], v[80:95]
	v_permlane32_swap_b32_e32 v100, v102
	v_permlane32_swap_b32_e32 v101, v103
	v_permlane32_swap_b32_e32 v104, v106
	v_permlane32_swap_b32_e32 v105, v107
	v_permlane32_swap_b32_e32 v108, v110
	s_waitcnt lgkmcnt(8)
	v_mfma_f32_32x32x16_bf16 v[64:79], v[166:169], v[134:137], v[64:79]
	v_permlane32_swap_b32_e32 v109, v111
	s_waitcnt vmcnt(0)
	ds_write_b128 v211, v[146:149] offset:16384
	s_nop 0
	s_waitcnt lgkmcnt(7)
	v_mfma_f32_32x32x16_bf16 v[0:15], v[96:99], v[180:183], v[0:15]
	ds_read_b64_tr_b16 v[180:181], v206 offset:0x8200
	ds_read_b64_tr_b16 v[182:183], v206 offset:0x8a00
	v_add_co_u32_e32 v166, vcc, s23, v178
	s_nop 1
	v_addc_co_u32_e32 v167, vcc, -1, v179, vcc
	v_add_co_u32_e32 v170, vcc, s24, v178
	s_nop 1
	v_addc_co_u32_e32 v171, vcc, -1, v179, vcc
	s_waitcnt lgkmcnt(7)
	v_mfma_f32_32x32x16_bf16 v[0:15], v[100:103], v[184:187], v[0:15]
	ds_read_b64_tr_b16 v[184:185], v206 offset:0x9200
	ds_read_b64_tr_b16 v[186:187], v206 offset:0x9a00
	global_load_dwordx4 v[162:165], v[166:167], off
	s_nop 0
	global_load_dwordx4 v[166:169], v[166:167], off offset:-512
	s_nop 0
	global_load_dwordx4 v[174:177], v[170:171], off
	s_nop 0
	global_load_dwordx4 v[170:173], v[170:171], off offset:-512
	s_waitcnt lgkmcnt(7)
; #define SBAR() __builtin_amdgcn_sched_barrier(0)
; template <int D0, int BOFF> __device__ __forceinline__ void pv_one_i(f32x16& od, int vb, bf16x8 pa0, bf16x8 pa1, bf16x8 pa2, bf16x8 pa3) {
;   const s16x4 l0 = tr_read<BOFF + v_rd_off(D0, 0, 0)>(vb), h0 = tr_read<BOFF + v_rd_off(D0, 0, 1)>(vb), l1 = tr_read<BOFF + v_rd_off(D0, 1, 0)>(vb), h1 = tr_read<BOFF + v_rd_off(D0, 1, 1)>(vb);
;   const s16x4 l2 = tr_read<BOFF + v_rd_off(D0, 2, 0)>(vb), h2 = tr_read<BOFF + v_rd_off(D0, 2, 1)>(vb), l3 = tr_read<BOFF + v_rd_off(D0, 3, 0)>(vb), h3 = tr_read<BOFF + v_rd_off(D0, 3, 1)>(vb);
;   asm volatile("s_waitcnt lgkmcnt(0)" ::: "memory"); SBAR();
;     ...
;   od = __builtin_amdgcn_mfma_f32_32x32x16_bf16(pa0, PK(l0, h0), od, 0, 0, 0);
;   od = __builtin_amdgcn_mfma_f32_32x32x16_bf16(pa1, PK(l1, h1), od, 0, 0, 0);
;   od = __builtin_amdgcn_mfma_f32_32x32x16_bf16(pa2, PK(l2, h2), od, 0, 0, 0);
;   od = __builtin_amdgcn_mfma_f32_32x32x16_bf16(pa3, PK(l3, h3), od, 0, 0, 0);
;     ...
; }
; template <int BOFF> __device__ __forceinline__ void pv_i(f32x16* o, int vb, bf16x8 pa0, bf16x8 pa1, bf16x8 pa2, bf16x8 pa3) {
;   pv_one_i<0, BOFF>(o[0], vb, pa0, pa1, pa2, pa3); pv_one_i<1, BOFF>(o[1], vb, pa0, pa1, pa2, pa3); pv_one_i<2, BOFF>(o[2], vb, pa0, pa1, pa2, pa3); pv_one_i<3, BOFF>(o[3], vb, pa0, pa1, pa2, pa3);
; }
	v_mfma_f32_32x32x16_bf16 v[0:15], v[104:107], v[216:219], v[0:15]
	ds_read_b64_tr_b16 v[216:217], v206 offset:0xa200
	ds_read_b64_tr_b16 v[218:219], v206 offset:0xaa00
	s_waitcnt lgkmcnt(7)
	v_mfma_f32_32x32x16_bf16 v[0:15], v[108:111], v[220:223], v[0:15]
	ds_read_b64_tr_b16 v[220:221], v206 offset:0xb200
	ds_read_b64_tr_b16 v[222:223], v206 offset:0xba00
	ds_write_b128 v212, v[158:161] offset:16384
	s_waitcnt lgkmcnt(7)
	v_mfma_f32_32x32x16_bf16 v[16:31], v[96:99], v[180:183], v[16:31]
	ds_read_b64_tr_b16 v[180:181], v206 offset:0x8400
	ds_read_b64_tr_b16 v[182:183], v206 offset:0x8c00
	v_exp_f32_e32 v200, v72
	v_exp_f32_e32 v201, v73
	s_waitcnt lgkmcnt(7)
	v_mfma_f32_32x32x16_bf16 v[16:31], v[100:103], v[184:187], v[16:31]
	ds_read_b64_tr_b16 v[184:185], v206 offset:0x9400
	ds_read_b64_tr_b16 v[186:187], v206 offset:0x9c00
	v_exp_f32_e32 v202, v74
	v_exp_f32_e32 v203, v75
	s_waitcnt lgkmcnt(7)
	v_mfma_f32_32x32x16_bf16 v[16:31], v[104:107], v[216:219], v[16:31]
	ds_read_b64_tr_b16 v[216:217], v206 offset:0xa400
	ds_read_b64_tr_b16 v[218:219], v206 offset:0xac00
	v_exp_f32_e32 v204, v76
	v_exp_f32_e32 v205, v77
	s_waitcnt lgkmcnt(7)
	v_mfma_f32_32x32x16_bf16 v[16:31], v[108:111], v[220:223], v[16:31]
	ds_read_b64_tr_b16 v[220:221], v206 offset:0xb400
	ds_read_b64_tr_b16 v[222:223], v206 offset:0xbc00
	v_exp_f32_e32 v240, v78
	v_exp_f32_e32 v241, v79
	ds_write_b128 v213, v[150:153] offset:16384
	s_waitcnt lgkmcnt(7)
	v_mfma_f32_32x32x16_bf16 v[32:47], v[96:99], v[180:183], v[32:47]
	ds_read_b64_tr_b16 v[180:181], v206 offset:0x8600
	ds_read_b64_tr_b16 v[182:183], v206 offset:0x8e00
	v_exp_f32_e32 v215, v92
	v_exp_f32_e32 v188, v86
	s_waitcnt lgkmcnt(7)
	v_mfma_f32_32x32x16_bf16 v[32:47], v[100:103], v[184:187], v[32:47]
	ds_read_b64_tr_b16 v[184:185], v206 offset:0x9600
	ds_read_b64_tr_b16 v[186:187], v206 offset:0x9e00
	v_exp_f32_e32 v189, v87
	v_exp_f32_e32 v196, v88
	s_waitcnt lgkmcnt(7)
	v_mfma_f32_32x32x16_bf16 v[32:47], v[104:107], v[216:219], v[32:47]
	ds_read_b64_tr_b16 v[216:217], v206 offset:0xa600
	ds_read_b64_tr_b16 v[218:219], v206 offset:0xae00
	v_exp_f32_e32 v197, v89
	v_exp_f32_e32 v198, v90
	s_waitcnt lgkmcnt(7)
	v_mfma_f32_32x32x16_bf16 v[32:47], v[108:111], v[220:223], v[32:47]
	ds_read_b64_tr_b16 v[220:221], v206 offset:0xb600
	ds_read_b64_tr_b16 v[222:223], v206 offset:0xbe00
	v_exp_f32_e32 v199, v91
	ds_write_b128 v214, v[154:157] offset:16384
	s_waitcnt lgkmcnt(7)
	v_mfma_f32_32x32x16_bf16 v[48:63], v[96:99], v[180:183], v[48:63]
	s_waitcnt vmcnt(4)
	v_exp_f32_e32 v181, v80
	v_exp_f32_e32 v183, v81
	s_waitcnt lgkmcnt(5)
	v_mfma_f32_32x32x16_bf16 v[48:63], v[100:103], v[184:187], v[48:63]
	v_exp_f32_e32 v184, v82
	v_exp_f32_e32 v185, v83
	v_exp_f32_e32 v186, v84
	v_exp_f32_e32 v187, v85
	s_waitcnt lgkmcnt(3)
	v_mfma_f32_32x32x16_bf16 v[48:63], v[104:107], v[216:219], v[48:63]
	v_exp_f32_e32 v216, v93
	v_exp_f32_e32 v217, v94
	v_exp_f32_e32 v218, v95
	s_waitcnt lgkmcnt(0)
	s_barrier
	v_mfma_f32_32x32x16_bf16 v[48:63], v[108:111], v[220:223], v[48:63]
	ds_read_b128 v[80:83], v207 offset:16384
	ds_read_b128 v[96:99], v207 offset:24576
	ds_read_b128 v[146:149], v208 offset:16384
	ds_read_b128 v[150:153], v208 offset:24576
	s_waitcnt lgkmcnt(3)
	v_mfma_f32_32x32x16_bf16 v[80:95], v[80:83], v[142:145], 0
	v_exp_f32_e32 v236, v64
	v_add_f32_e32 v64, 0, v181
	v_add_f32_e32 v64, v183, v64
	v_add_f32_e32 v64, v184, v64
	s_waitcnt lgkmcnt(2)
	v_mfma_f32_32x32x16_bf16 v[96:111], v[96:99], v[142:145], 0
	v_add_f32_e32 v64, v185, v64
	v_add_f32_e32 v64, v186, v64
	v_add_f32_e32 v64, v187, v64
	s_waitcnt lgkmcnt(1)
	v_mfma_f32_32x32x16_bf16 v[80:95], v[146:149], v[138:141], v[80:95]
	v_add_f32_e32 v64, v188, v64
	v_add_f32_e32 v64, v189, v64
	v_add_f32_e32 v64, v196, v64
	s_waitcnt lgkmcnt(0)
	v_mfma_f32_32x32x16_bf16 v[96:111], v[150:153], v[138:141], v[96:111]
	ds_read_b128 v[146:149], v209 offset:16384
	ds_read_b128 v[150:153], v209 offset:24576
	v_add_f32_e32 v64, v197, v64
	v_add_f32_e32 v64, v198, v64
	v_add_f32_e32 v64, v199, v64
	v_add_f32_e32 v64, v215, v64
	v_exp_f32_e32 v237, v65
	s_waitcnt lgkmcnt(1)
	v_mfma_f32_32x32x16_bf16 v[80:95], v[146:149], v[112:115], v[80:95]
	v_add_f32_e32 v64, v216, v64
	v_exp_f32_e32 v238, v66
	v_add_f32_e32 v64, v217, v64
	v_exp_f32_e32 v239, v67
	s_waitcnt lgkmcnt(0)
	v_mfma_f32_32x32x16_bf16 v[96:111], v[150:153], v[112:115], v[96:111]
	ds_read_b128 v[146:149], v210 offset:16384
	ds_read_b128 v[150:153], v210 offset:24576
	v_add_f32_e32 v64, v218, v64
	v_exp_f32_e32 v247, v68
	v_add_f32_e32 v64, v236, v64
	v_exp_f32_e32 v248, v69
	s_waitcnt lgkmcnt(1)
	v_mfma_f32_32x32x16_bf16 v[80:95], v[146:149], v[116:119], v[80:95]
	v_add_f32_e32 v64, v237, v64
	v_exp_f32_e32 v249, v70
	v_add_f32_e32 v64, v238, v64
	v_exp_f32_e32 v252, v71
	s_waitcnt lgkmcnt(0)
	v_mfma_f32_32x32x16_bf16 v[96:111], v[150:153], v[116:119], v[96:111]
	ds_read_b128 v[146:149], v190 offset:16384
	ds_read_b128 v[150:153], v190 offset:24576
	v_add_f32_e32 v64, v239, v64
	v_add_f32_e32 v64, v247, v64
	v_add_f32_e32 v64, v248, v64
	v_add_f32_e32 v64, v249, v64
	v_add_f32_e32 v64, v252, v64
	v_add_f32_e32 v64, v200, v64
	s_waitcnt lgkmcnt(1)
	v_mfma_f32_32x32x16_bf16 v[80:95], v[146:149], v[120:123], v[80:95]
	v_add_f32_e32 v64, v201, v64
	v_add_f32_e32 v64, v202, v64
	v_add_f32_e32 v64, v203, v64
	v_add_f32_e32 v64, v204, v64
	v_add_f32_e32 v64, v205, v64
	s_waitcnt lgkmcnt(0)
	v_mfma_f32_32x32x16_bf16 v[96:111], v[150:153], v[120:123], v[96:111]
	ds_read_b128 v[146:149], v191 offset:16384
	ds_read_b128 v[150:153], v191 offset:24576
	v_add_f32_e32 v64, v240, v64
	v_add_f32_e32 v180, v241, v64
	v_cvt_pk_bf16_f32 v64, v181, v183
	v_cvt_pk_bf16_f32 v65, v184, v185
	v_cvt_pk_bf16_f32 v66, v186, v187
	v_cvt_pk_bf16_f32 v67, v188, v189
	s_waitcnt lgkmcnt(1)
; #define SBAR() __builtin_amdgcn_sched_barrier(0)
; template <int D0, int BOFF> __device__ __forceinline__ void pv_one_i(f32x16& od, int vb, bf16x8 pa0, bf16x8 pa1, bf16x8 pa2, bf16x8 pa3) {
;   const s16x4 l0 = tr_read<BOFF + v_rd_off(D0, 0, 0)>(vb), h0 = tr_read<BOFF + v_rd_off(D0, 0, 1)>(vb), l1 = tr_read<BOFF + v_rd_off(D0, 1, 0)>(vb), h1 = tr_read<BOFF + v_rd_off(D0, 1, 1)>(vb);
;   const s16x4 l2 = tr_read<BOFF + v_rd_off(D0, 2, 0)>(vb), h2 = tr_read<BOFF + v_rd_off(D0, 2, 1)>(vb), l3 = tr_read<BOFF + v_rd_off(D0, 3, 0)>(vb), h3 = tr_read<BOFF + v_rd_off(D0, 3, 1)>(vb);
;   asm volatile("s_waitcnt lgkmcnt(0)" ::: "memory"); SBAR();
;     ...
;   od = __builtin_amdgcn_mfma_f32_32x32x16_bf16(pa0, PK(l0, h0), od, 0, 0, 0);
;   od = __builtin_amdgcn_mfma_f32_32x32x16_bf16(pa1, PK(l1, h1), od, 0, 0, 0);
;   od = __builtin_amdgcn_mfma_f32_32x32x16_bf16(pa2, PK(l2, h2), od, 0, 0, 0);
;   od = __builtin_amdgcn_mfma_f32_32x32x16_bf16(pa3, PK(l3, h3), od, 0, 0, 0);
;     ...
; }
; template <int BOFF> __device__ __forceinline__ void pv_i(f32x16* o, int vb, bf16x8 pa0, bf16x8 pa1, bf16x8 pa2, bf16x8 pa3) {
;   pv_one_i<0, BOFF>(o[0], vb, pa0, pa1, pa2, pa3); pv_one_i<1, BOFF>(o[1], vb, pa0, pa1, pa2, pa3); pv_one_i<2, BOFF>(o[2], vb, pa0, pa1, pa2, pa3); pv_one_i<3, BOFF>(o[3], vb, pa0, pa1, pa2, pa3);
; }
	v_mfma_f32_32x32x16_bf16 v[80:95], v[146:149], v[124:127], v[80:95]
	v_cvt_pk_bf16_f32 v68, v196, v197
	v_cvt_pk_bf16_f32 v69, v198, v199
	v_cvt_pk_bf16_f32 v70, v215, v216
	v_cvt_pk_bf16_f32 v71, v217, v218
	v_cvt_pk_bf16_f32 v72, v236, v237
	s_waitcnt lgkmcnt(0)
	v_mfma_f32_32x32x16_bf16 v[96:111], v[150:153], v[124:127], v[96:111]
	ds_read_b128 v[146:149], v192 offset:16384
	ds_read_b128 v[150:153], v192 offset:24576
	v_cvt_pk_bf16_f32 v73, v238, v239
	v_cvt_pk_bf16_f32 v74, v247, v248
	v_cvt_pk_bf16_f32 v75, v249, v252
	v_cvt_pk_bf16_f32 v76, v200, v201
	v_cvt_pk_bf16_f32 v77, v202, v203
	v_cvt_pk_bf16_f32 v78, v204, v205
	s_waitcnt lgkmcnt(1)
	v_mfma_f32_32x32x16_bf16 v[80:95], v[146:149], v[130:133], v[80:95]
	v_cvt_pk_bf16_f32 v79, v240, v241
	v_mov_b32_e32 v182, v180
	v_permlane32_swap_b32_e32 v64, v66
	v_permlane32_swap_b32_e32 v65, v67
	v_permlane32_swap_b32_e32 v68, v70
	s_waitcnt lgkmcnt(0)
	v_mfma_f32_32x32x16_bf16 v[96:111], v[150:153], v[130:133], v[96:111]
	ds_read_b128 v[146:149], v193 offset:16384
	ds_read_b128 v[150:153], v193 offset:24576
	ds_read_b64_tr_b16 v[184:185], v206 offset:0
	ds_read_b64_tr_b16 v[186:187], v206 offset:0x800
	ds_read_b64_tr_b16 v[216:217], v206 offset:0x1000
	ds_read_b64_tr_b16 v[218:219], v206 offset:0x1800
	ds_read_b64_tr_b16 v[220:221], v206 offset:0x2000
	ds_read_b64_tr_b16 v[222:223], v206 offset:0x2800
	ds_read_b64_tr_b16 v[224:225], v206 offset:0x3000
	ds_read_b64_tr_b16 v[226:227], v206 offset:0x3800
	v_permlane32_swap_b32_e32 v69, v71
	v_permlane32_swap_b32_e32 v72, v74
	v_permlane32_swap_b32_e32 v73, v75
	v_permlane32_swap_b32_e32 v76, v78
	v_permlane32_swap_b32_e32 v77, v79
	v_permlane32_swap_b32_e32 v180, v182
	s_waitcnt lgkmcnt(9)
	v_mfma_f32_32x32x16_bf16 v[80:95], v[146:149], v[134:137], v[80:95]
	s_waitcnt lgkmcnt(8)
	v_mfma_f32_32x32x16_bf16 v[96:111], v[150:153], v[134:137], v[96:111]
	s_waitcnt vmcnt(0)
	ds_write_b128 v211, v[162:165] offset:32768
	s_nop 0
	s_waitcnt lgkmcnt(7)
	v_mfma_f32_32x32x16_bf16 v[0:15], v[64:67], v[184:187], v[0:15]
	ds_read_b64_tr_b16 v[184:185], v206 offset:0x200
	ds_read_b64_tr_b16 v[186:187], v206 offset:0xa00
	v_add_co_u32_e32 v150, vcc, s25, v178
	s_nop 1
	v_addc_co_u32_e32 v151, vcc, -1, v179, vcc
	v_add_co_u32_e32 v154, vcc, s45, v178
	s_nop 1
	v_addc_co_u32_e32 v155, vcc, -1, v179, vcc
	s_waitcnt lgkmcnt(7)
	v_mfma_f32_32x32x16_bf16 v[0:15], v[68:71], v[216:219], v[0:15]
	ds_read_b64_tr_b16 v[216:217], v206 offset:0x1200
	ds_read_b64_tr_b16 v[218:219], v206 offset:0x1a00
	global_load_dwordx4 v[146:149], v[150:151], off
	s_nop 0
	global_load_dwordx4 v[150:153], v[150:151], off offset:-512
	s_nop 0
	global_load_dwordx4 v[158:161], v[154:155], off
	s_nop 0
	global_load_dwordx4 v[154:157], v[154:155], off offset:-512
	s_waitcnt lgkmcnt(7)
	v_mfma_f32_32x32x16_bf16 v[0:15], v[72:75], v[220:223], v[0:15]
	ds_read_b64_tr_b16 v[220:221], v206 offset:0x2200
	ds_read_b64_tr_b16 v[222:223], v206 offset:0x2a00
	s_waitcnt lgkmcnt(7)
	v_mfma_f32_32x32x16_bf16 v[0:15], v[76:79], v[224:227], v[0:15]
	ds_read_b64_tr_b16 v[224:225], v206 offset:0x3200
	ds_read_b64_tr_b16 v[226:227], v206 offset:0x3a00
	ds_write_b128 v212, v[174:177] offset:32768
	s_waitcnt lgkmcnt(7)
	v_mfma_f32_32x32x16_bf16 v[16:31], v[64:67], v[184:187], v[16:31]
	ds_read_b64_tr_b16 v[184:185], v206 offset:0x400
	ds_read_b64_tr_b16 v[186:187], v206 offset:0xc00
	v_exp_f32_e32 v200, v104
	v_exp_f32_e32 v201, v105
	s_waitcnt lgkmcnt(7)
	v_mfma_f32_32x32x16_bf16 v[16:31], v[68:71], v[216:219], v[16:31]
	ds_read_b64_tr_b16 v[216:217], v206 offset:0x1400
	ds_read_b64_tr_b16 v[218:219], v206 offset:0x1c00
	v_exp_f32_e32 v202, v106
	v_exp_f32_e32 v203, v107
	s_waitcnt lgkmcnt(7)
	v_mfma_f32_32x32x16_bf16 v[16:31], v[72:75], v[220:223], v[16:31]
	ds_read_b64_tr_b16 v[220:221], v206 offset:0x2400
	ds_read_b64_tr_b16 v[222:223], v206 offset:0x2c00
	v_exp_f32_e32 v204, v108
	v_exp_f32_e32 v205, v109
	s_waitcnt lgkmcnt(7)
	v_mfma_f32_32x32x16_bf16 v[16:31], v[76:79], v[224:227], v[16:31]
	ds_read_b64_tr_b16 v[224:225], v206 offset:0x3400
	ds_read_b64_tr_b16 v[226:227], v206 offset:0x3c00
	v_exp_f32_e32 v240, v110
	v_exp_f32_e32 v241, v111
	ds_write_b128 v213, v[166:169] offset:32768
	s_waitcnt lgkmcnt(7)
	v_mfma_f32_32x32x16_bf16 v[32:47], v[64:67], v[184:187], v[32:47]
	ds_read_b64_tr_b16 v[184:185], v206 offset:0x600
	ds_read_b64_tr_b16 v[186:187], v206 offset:0xe00
	v_exp_f32_e32 v215, v90
	v_exp_f32_e32 v188, v84
	s_waitcnt lgkmcnt(7)
	v_mfma_f32_32x32x16_bf16 v[32:47], v[68:71], v[216:219], v[32:47]
	ds_read_b64_tr_b16 v[216:217], v206 offset:0x1600
	ds_read_b64_tr_b16 v[218:219], v206 offset:0x1e00
	v_exp_f32_e32 v189, v85
	v_exp_f32_e32 v196, v86
	s_waitcnt lgkmcnt(7)
	v_mfma_f32_32x32x16_bf16 v[32:47], v[72:75], v[220:223], v[32:47]
	ds_read_b64_tr_b16 v[220:221], v206 offset:0x2600
	ds_read_b64_tr_b16 v[222:223], v206 offset:0x2e00
	v_exp_f32_e32 v197, v87
	v_exp_f32_e32 v198, v88
	s_waitcnt lgkmcnt(7)
	v_mfma_f32_32x32x16_bf16 v[32:47], v[76:79], v[224:227], v[32:47]
	ds_read_b64_tr_b16 v[224:225], v206 offset:0x3600
	ds_read_b64_tr_b16 v[226:227], v206 offset:0x3e00
	v_exp_f32_e32 v199, v89
	ds_write_b128 v214, v[170:173] offset:32768
	s_waitcnt lgkmcnt(7)
	v_mfma_f32_32x32x16_bf16 v[48:63], v[64:67], v[184:187], v[48:63]
	s_waitcnt vmcnt(4)
	v_exp_f32_e32 v184, v80
	v_exp_f32_e32 v185, v81
	v_exp_f32_e32 v186, v82
	v_exp_f32_e32 v187, v83
	s_waitcnt lgkmcnt(5)
	v_mfma_f32_32x32x16_bf16 v[48:63], v[68:71], v[216:219], v[48:63]
	v_exp_f32_e32 v219, v94
	v_exp_f32_e32 v216, v91
	s_waitcnt lgkmcnt(3)
	v_mfma_f32_32x32x16_bf16 v[48:63], v[72:75], v[220:223], v[48:63]
	v_exp_f32_e32 v220, v95
	v_exp_f32_e32 v217, v92
	v_exp_f32_e32 v218, v93
	s_waitcnt lgkmcnt(0)
	s_barrier
; __device__ __forceinline__ void finishSM(f32x16& p0, f32x16& p1, float alpha, float& l_reg, bf16x8& pa0, bf16x8& pa1, bf16x8& pa2, bf16x8& pa3) {
;   for (int r = 0; r < 16; ++r) p1[r] = __builtin_amdgcn_exp2f(p1[r]);
;   float ps = 0; for (int r = 0; r < 16; ++r) ps += p0[r]; for (int r = 0; r < 16; ++r) ps += p1[r];
;   { auto rr = __builtin_amdgcn_permlane32_swap(__float_as_uint(ps), __float_as_uint(ps), false, false);
;     ps = __uint_as_float(rr[0]) + __uint_as_float(rr[1]); }
;   l_reg = l_reg * alpha + ps;
;     ...
;   PK4(p0, 0, pa0); PK4(p0, 8, pa1); PK4(p1, 0, pa2); PK4(p1, 8, pa3);
;     ...
; }
	v_mfma_f32_32x32x16_bf16 v[48:63], v[76:79], v[224:227], v[48:63]
	ds_read_b128 v[64:67], v207 offset:32768
	ds_read_b128 v[80:83], v207 offset:40960
	ds_read_b128 v[162:165], v208 offset:32768
	ds_read_b128 v[166:169], v208 offset:40960
	s_waitcnt lgkmcnt(3)
	v_mfma_f32_32x32x16_bf16 v[64:79], v[64:67], v[142:145], 0
	v_exp_f32_e32 v236, v96
	v_add_f32_e32 v96, 0, v184
	v_add_f32_e32 v96, v185, v96
	v_add_f32_e32 v96, v186, v96
	s_waitcnt lgkmcnt(2)
	v_mfma_f32_32x32x16_bf16 v[80:95], v[80:83], v[142:145], 0
	v_add_f32_e32 v96, v187, v96
	v_add_f32_e32 v96, v188, v96
	v_add_f32_e32 v96, v189, v96
	s_waitcnt lgkmcnt(1)
	v_mfma_f32_32x32x16_bf16 v[64:79], v[162:165], v[138:141], v[64:79]
	v_add_f32_e32 v96, v196, v96
	v_add_f32_e32 v96, v197, v96
	v_add_f32_e32 v96, v198, v96
	s_waitcnt lgkmcnt(0)
	v_mfma_f32_32x32x16_bf16 v[80:95], v[166:169], v[138:141], v[80:95]
	ds_read_b128 v[162:165], v209 offset:32768
	ds_read_b128 v[166:169], v209 offset:40960
	v_add_f32_e32 v96, v199, v96
	v_add_f32_e32 v96, v215, v96
	v_add_f32_e32 v96, v216, v96
	v_add_f32_e32 v96, v217, v96
	v_exp_f32_e32 v237, v97
	s_waitcnt lgkmcnt(1)
	v_mfma_f32_32x32x16_bf16 v[64:79], v[162:165], v[112:115], v[64:79]
	v_add_f32_e32 v96, v218, v96
	v_exp_f32_e32 v238, v98
	v_add_f32_e32 v96, v219, v96
	v_exp_f32_e32 v239, v99
	s_waitcnt lgkmcnt(0)
	v_mfma_f32_32x32x16_bf16 v[80:95], v[166:169], v[112:115], v[80:95]
	ds_read_b128 v[162:165], v210 offset:32768
	ds_read_b128 v[166:169], v210 offset:40960
	v_add_f32_e32 v96, v220, v96
	v_exp_f32_e32 v247, v100
	v_add_f32_e32 v96, v236, v96
	v_exp_f32_e32 v248, v101
	s_waitcnt lgkmcnt(1)
	v_mfma_f32_32x32x16_bf16 v[64:79], v[162:165], v[116:119], v[64:79]
	v_add_f32_e32 v96, v237, v96
	v_exp_f32_e32 v249, v102
	v_add_f32_e32 v96, v238, v96
	v_exp_f32_e32 v252, v103
	s_waitcnt lgkmcnt(0)
	v_mfma_f32_32x32x16_bf16 v[80:95], v[166:169], v[116:119], v[80:95]
	ds_read_b128 v[162:165], v190 offset:32768
	ds_read_b128 v[166:169], v190 offset:40960
	v_add_f32_e32 v96, v239, v96
	v_add_f32_e32 v96, v247, v96
	v_add_f32_e32 v96, v248, v96
	v_add_f32_e32 v96, v249, v96
	v_add_f32_e32 v96, v252, v96
	v_add_f32_e32 v96, v200, v96
	s_waitcnt lgkmcnt(1)
	v_mfma_f32_32x32x16_bf16 v[64:79], v[162:165], v[120:123], v[64:79]
	v_add_f32_e32 v96, v201, v96
	v_add_f32_e32 v96, v202, v96
	v_add_f32_e32 v96, v203, v96
	v_add_f32_e32 v96, v204, v96
	v_add_f32_e32 v96, v205, v96
	s_waitcnt lgkmcnt(0)
	v_mfma_f32_32x32x16_bf16 v[80:95], v[166:169], v[120:123], v[80:95]
	ds_read_b128 v[162:165], v191 offset:32768
	ds_read_b128 v[166:169], v191 offset:40960
	v_add_f32_e32 v96, v240, v96
	v_add_f32_e32 v181, v241, v96
	v_mov_b32_e32 v183, v181
	s_nop 1
	v_permlane32_swap_b32_e32 v181, v183
	v_pk_add_f32 v[96:97], v[180:181], v[182:183]
	s_waitcnt lgkmcnt(1)
	v_mfma_f32_32x32x16_bf16 v[64:79], v[162:165], v[124:127], v[64:79]
	s_nop 0
	v_add_f32_e32 v96, v128, v96
	v_add_f32_e32 v128, v96, v97
	v_cvt_pk_bf16_f32 v96, v184, v185
	v_cvt_pk_bf16_f32 v97, v186, v187
	s_waitcnt lgkmcnt(0)
	v_mfma_f32_32x32x16_bf16 v[80:95], v[166:169], v[124:127], v[80:95]
	ds_read_b128 v[162:165], v192 offset:32768
	ds_read_b128 v[166:169], v192 offset:40960
	v_cvt_pk_bf16_f32 v98, v188, v189
	v_cvt_pk_bf16_f32 v99, v196, v197
	v_cvt_pk_bf16_f32 v100, v198, v199
	v_cvt_pk_bf16_f32 v101, v215, v216
	v_cvt_pk_bf16_f32 v102, v217, v218
	v_cvt_pk_bf16_f32 v103, v219, v220
	s_waitcnt lgkmcnt(1)
	v_mfma_f32_32x32x16_bf16 v[64:79], v[162:165], v[130:133], v[64:79]
	v_cvt_pk_bf16_f32 v104, v236, v237
	v_cvt_pk_bf16_f32 v105, v238, v239
	v_cvt_pk_bf16_f32 v106, v247, v248
	v_cvt_pk_bf16_f32 v107, v249, v252
	v_cvt_pk_bf16_f32 v108, v200, v201
	s_waitcnt lgkmcnt(0)
	v_mfma_f32_32x32x16_bf16 v[80:95], v[166:169], v[130:133], v[80:95]
	ds_read_b128 v[162:165], v193 offset:32768
	ds_read_b128 v[166:169], v193 offset:40960
	ds_read_b64_tr_b16 v[180:181], v206 offset:0x4000
	ds_read_b64_tr_b16 v[182:183], v206 offset:0x4800
	ds_read_b64_tr_b16 v[184:185], v206 offset:0x5000
	ds_read_b64_tr_b16 v[186:187], v206 offset:0x5800
	ds_read_b64_tr_b16 v[216:217], v206 offset:0x6000
	ds_read_b64_tr_b16 v[218:219], v206 offset:0x6800
	ds_read_b64_tr_b16 v[220:221], v206 offset:0x7000
	ds_read_b64_tr_b16 v[222:223], v206 offset:0x7800
	v_cvt_pk_bf16_f32 v109, v202, v203
	v_cvt_pk_bf16_f32 v110, v204, v205
	v_cvt_pk_bf16_f32 v111, v240, v241
	s_nop 0
	v_permlane32_swap_b32_e32 v96, v98
	v_permlane32_swap_b32_e32 v97, v99
	s_waitcnt lgkmcnt(9)
	v_mfma_f32_32x32x16_bf16 v[64:79], v[162:165], v[134:137], v[64:79]
	v_permlane32_swap_b32_e32 v100, v102
	v_permlane32_swap_b32_e32 v101, v103
	v_permlane32_swap_b32_e32 v104, v106
	v_permlane32_swap_b32_e32 v105, v107
	v_permlane32_swap_b32_e32 v108, v110
	s_waitcnt lgkmcnt(8)
	v_mfma_f32_32x32x16_bf16 v[80:95], v[166:169], v[134:137], v[80:95]
	v_permlane32_swap_b32_e32 v109, v111
	s_waitcnt vmcnt(0)
	ds_write_b128 v211, v[146:149]
	s_nop 0
	s_waitcnt lgkmcnt(7)
	v_mfma_f32_32x32x16_bf16 v[0:15], v[96:99], v[180:183], v[0:15]
	ds_read_b64_tr_b16 v[180:181], v206 offset:0x4200
	ds_read_b64_tr_b16 v[182:183], v206 offset:0x4a00
	v_add_co_u32_e32 v166, vcc, s52, v178
	s_nop 1
	v_addc_co_u32_e32 v167, vcc, -1, v179, vcc
	v_add_co_u32_e32 v170, vcc, s53, v178
	s_nop 1
	v_addc_co_u32_e32 v171, vcc, -1, v179, vcc
	s_waitcnt lgkmcnt(7)
	v_mfma_f32_32x32x16_bf16 v[0:15], v[100:103], v[184:187], v[0:15]
	ds_read_b64_tr_b16 v[184:185], v206 offset:0x5200
	ds_read_b64_tr_b16 v[186:187], v206 offset:0x5a00
	global_load_dwordx4 v[162:165], v[166:167], off
	s_nop 0
	global_load_dwordx4 v[166:169], v[166:167], off offset:-512
	s_nop 0
	global_load_dwordx4 v[174:177], v[170:171], off
	s_nop 0
	global_load_dwordx4 v[170:173], v[170:171], off offset:-512
	s_waitcnt lgkmcnt(7)
; #define SBAR() __builtin_amdgcn_sched_barrier(0)
; template <int D0, int BOFF> __device__ __forceinline__ void pv_one_i(f32x16& od, int vb, bf16x8 pa0, bf16x8 pa1, bf16x8 pa2, bf16x8 pa3) {
;   const s16x4 l0 = tr_read<BOFF + v_rd_off(D0, 0, 0)>(vb), h0 = tr_read<BOFF + v_rd_off(D0, 0, 1)>(vb), l1 = tr_read<BOFF + v_rd_off(D0, 1, 0)>(vb), h1 = tr_read<BOFF + v_rd_off(D0, 1, 1)>(vb);
;   const s16x4 l2 = tr_read<BOFF + v_rd_off(D0, 2, 0)>(vb), h2 = tr_read<BOFF + v_rd_off(D0, 2, 1)>(vb), l3 = tr_read<BOFF + v_rd_off(D0, 3, 0)>(vb), h3 = tr_read<BOFF + v_rd_off(D0, 3, 1)>(vb);
;   asm volatile("s_waitcnt lgkmcnt(0)" ::: "memory"); SBAR();
;     ...
;   od = __builtin_amdgcn_mfma_f32_32x32x16_bf16(pa0, PK(l0, h0), od, 0, 0, 0);
;   od = __builtin_amdgcn_mfma_f32_32x32x16_bf16(pa1, PK(l1, h1), od, 0, 0, 0);
;   od = __builtin_amdgcn_mfma_f32_32x32x16_bf16(pa2, PK(l2, h2), od, 0, 0, 0);
;   od = __builtin_amdgcn_mfma_f32_32x32x16_bf16(pa3, PK(l3, h3), od, 0, 0, 0);
;     ...
; }
; template <int BOFF> __device__ __forceinline__ void pv_i(f32x16* o, int vb, bf16x8 pa0, bf16x8 pa1, bf16x8 pa2, bf16x8 pa3) {
;   pv_one_i<0, BOFF>(o[0], vb, pa0, pa1, pa2, pa3); pv_one_i<1, BOFF>(o[1], vb, pa0, pa1, pa2, pa3); pv_one_i<2, BOFF>(o[2], vb, pa0, pa1, pa2, pa3); pv_one_i<3, BOFF>(o[3], vb, pa0, pa1, pa2, pa3);
; }
	v_mfma_f32_32x32x16_bf16 v[0:15], v[104:107], v[216:219], v[0:15]
	ds_read_b64_tr_b16 v[216:217], v206 offset:0x6200
	ds_read_b64_tr_b16 v[218:219], v206 offset:0x6a00
	s_waitcnt lgkmcnt(7)
	v_mfma_f32_32x32x16_bf16 v[0:15], v[108:111], v[220:223], v[0:15]
	ds_read_b64_tr_b16 v[220:221], v206 offset:0x7200
	ds_read_b64_tr_b16 v[222:223], v206 offset:0x7a00
	ds_write_b128 v212, v[158:161]
	s_waitcnt lgkmcnt(7)
	v_mfma_f32_32x32x16_bf16 v[16:31], v[96:99], v[180:183], v[16:31]
	ds_read_b64_tr_b16 v[180:181], v206 offset:0x4400
	ds_read_b64_tr_b16 v[182:183], v206 offset:0x4c00
	v_exp_f32_e32 v200, v88
	v_exp_f32_e32 v201, v89
	s_waitcnt lgkmcnt(7)
	v_mfma_f32_32x32x16_bf16 v[16:31], v[100:103], v[184:187], v[16:31]
	ds_read_b64_tr_b16 v[184:185], v206 offset:0x5400
	ds_read_b64_tr_b16 v[186:187], v206 offset:0x5c00
	v_exp_f32_e32 v202, v90
	v_exp_f32_e32 v203, v91
	s_waitcnt lgkmcnt(7)
	v_mfma_f32_32x32x16_bf16 v[16:31], v[104:107], v[216:219], v[16:31]
	ds_read_b64_tr_b16 v[216:217], v206 offset:0x6400
	ds_read_b64_tr_b16 v[218:219], v206 offset:0x6c00
	v_exp_f32_e32 v204, v92
	v_exp_f32_e32 v205, v93
	s_waitcnt lgkmcnt(7)
	v_mfma_f32_32x32x16_bf16 v[16:31], v[108:111], v[220:223], v[16:31]
	ds_read_b64_tr_b16 v[220:221], v206 offset:0x7400
	ds_read_b64_tr_b16 v[222:223], v206 offset:0x7c00
	v_exp_f32_e32 v240, v94
	v_exp_f32_e32 v241, v95
	ds_write_b128 v213, v[150:153]
	s_waitcnt lgkmcnt(7)
	v_mfma_f32_32x32x16_bf16 v[32:47], v[96:99], v[180:183], v[32:47]
	ds_read_b64_tr_b16 v[180:181], v206 offset:0x4600
	ds_read_b64_tr_b16 v[182:183], v206 offset:0x4e00
	v_exp_f32_e32 v188, v72
	v_exp_f32_e32 v189, v73
	s_waitcnt lgkmcnt(7)
	v_mfma_f32_32x32x16_bf16 v[32:47], v[100:103], v[184:187], v[32:47]
	ds_read_b64_tr_b16 v[184:185], v206 offset:0x5600
	ds_read_b64_tr_b16 v[186:187], v206 offset:0x5e00
	v_exp_f32_e32 v196, v74
	v_exp_f32_e32 v197, v75
	s_waitcnt lgkmcnt(7)
	v_mfma_f32_32x32x16_bf16 v[32:47], v[104:107], v[216:219], v[32:47]
	ds_read_b64_tr_b16 v[216:217], v206 offset:0x6600
	ds_read_b64_tr_b16 v[218:219], v206 offset:0x6e00
	v_exp_f32_e32 v198, v76
	v_exp_f32_e32 v199, v77
	s_waitcnt lgkmcnt(7)
	v_mfma_f32_32x32x16_bf16 v[32:47], v[108:111], v[220:223], v[32:47]
	ds_read_b64_tr_b16 v[220:221], v206 offset:0x7600
	ds_read_b64_tr_b16 v[222:223], v206 offset:0x7e00
	ds_write_b128 v214, v[154:157]
	s_waitcnt lgkmcnt(7)
	v_mfma_f32_32x32x16_bf16 v[48:63], v[96:99], v[180:183], v[48:63]
	s_waitcnt vmcnt(4)
	v_exp_f32_e32 v180, v64
	v_exp_f32_e32 v181, v65
	v_exp_f32_e32 v182, v66
	v_exp_f32_e32 v183, v67
	s_waitcnt lgkmcnt(5)
	v_mfma_f32_32x32x16_bf16 v[48:63], v[100:103], v[184:187], v[48:63]
	v_exp_f32_e32 v184, v68
	v_exp_f32_e32 v185, v69
	v_exp_f32_e32 v186, v70
	v_exp_f32_e32 v187, v71
	s_waitcnt lgkmcnt(3)
	v_mfma_f32_32x32x16_bf16 v[48:63], v[104:107], v[216:219], v[48:63]
	v_exp_f32_e32 v216, v78
	v_exp_f32_e32 v217, v79
	s_waitcnt lgkmcnt(0)
	s_barrier
	v_mfma_f32_32x32x16_bf16 v[48:63], v[108:111], v[220:223], v[48:63]
	ds_read_b128 v[64:67], v207
	ds_read_b128 v[68:71], v207 offset:8192
	ds_read_b128 v[146:149], v208
	ds_read_b128 v[150:153], v208 offset:8192
	s_waitcnt lgkmcnt(3)
	v_mfma_f32_32x32x16_bf16 v[96:111], v[64:67], v[142:145], 0
	v_exp_f32_e32 v236, v80
	v_add_f32_e32 v80, 0, v180
	v_add_f32_e32 v80, v181, v80
	v_add_f32_e32 v80, v182, v80
	s_waitcnt lgkmcnt(2)
	v_mfma_f32_32x32x16_bf16 v[64:79], v[68:71], v[142:145], 0
	v_add_f32_e32 v80, v183, v80
	v_add_f32_e32 v80, v184, v80
	v_add_f32_e32 v80, v185, v80
	s_waitcnt lgkmcnt(1)
	v_mfma_f32_32x32x16_bf16 v[96:111], v[146:149], v[138:141], v[96:111]
	v_add_f32_e32 v80, v186, v80
	v_add_f32_e32 v80, v187, v80
	v_add_f32_e32 v80, v188, v80
	s_waitcnt lgkmcnt(0)
	v_mfma_f32_32x32x16_bf16 v[64:79], v[150:153], v[138:141], v[64:79]
	ds_read_b128 v[146:149], v209
	ds_read_b128 v[150:153], v209 offset:8192
	v_add_f32_e32 v80, v189, v80
	v_add_f32_e32 v80, v196, v80
	v_add_f32_e32 v80, v197, v80
	v_add_f32_e32 v80, v198, v80
	v_exp_f32_e32 v237, v81
	s_waitcnt lgkmcnt(1)
	v_mfma_f32_32x32x16_bf16 v[96:111], v[146:149], v[112:115], v[96:111]
	v_add_f32_e32 v80, v199, v80
	v_exp_f32_e32 v238, v82
	v_add_f32_e32 v80, v216, v80
	v_exp_f32_e32 v239, v83
	s_waitcnt lgkmcnt(0)
	v_mfma_f32_32x32x16_bf16 v[64:79], v[150:153], v[112:115], v[64:79]
	ds_read_b128 v[146:149], v210
	ds_read_b128 v[150:153], v210 offset:8192
	v_add_f32_e32 v80, v217, v80
	v_exp_f32_e32 v247, v84
	v_add_f32_e32 v80, v236, v80
	v_exp_f32_e32 v248, v85
	s_waitcnt lgkmcnt(1)
	v_mfma_f32_32x32x16_bf16 v[96:111], v[146:149], v[116:119], v[96:111]
	v_add_f32_e32 v80, v237, v80
	v_exp_f32_e32 v249, v86
	v_add_f32_e32 v80, v238, v80
	v_exp_f32_e32 v252, v87
	s_waitcnt lgkmcnt(0)
	v_mfma_f32_32x32x16_bf16 v[64:79], v[150:153], v[116:119], v[64:79]
	ds_read_b128 v[146:149], v190 offset:0
	ds_read_b128 v[150:153], v190 offset:8192
	v_add_f32_e32 v80, v239, v80
	v_add_f32_e32 v80, v247, v80
	v_add_f32_e32 v80, v248, v80
	v_add_f32_e32 v80, v249, v80
	v_add_f32_e32 v80, v252, v80
	v_add_f32_e32 v80, v200, v80
	s_waitcnt lgkmcnt(1)
	v_mfma_f32_32x32x16_bf16 v[96:111], v[146:149], v[120:123], v[96:111]
	v_add_f32_e32 v80, v201, v80
	v_add_f32_e32 v80, v202, v80
	v_add_f32_e32 v80, v203, v80
	v_add_f32_e32 v80, v204, v80
	v_add_f32_e32 v80, v205, v80
	s_waitcnt lgkmcnt(0)
	v_mfma_f32_32x32x16_bf16 v[64:79], v[150:153], v[120:123], v[64:79]
	ds_read_b128 v[146:149], v191 offset:0
	ds_read_b128 v[150:153], v191 offset:8192
	v_add_f32_e32 v80, v240, v80
	v_add_f32_e32 v80, v241, v80
	v_mov_b32_e32 v81, v80
	s_nop 1
	v_permlane32_swap_b32_e32 v80, v81
	v_add_f32_e32 v80, v80, v81
	s_waitcnt lgkmcnt(1)
; #define SLOAD(i, k0) do { sr_[i].vs0 = ld8(&Vh[(long)((k0) + sr) * LDK + sc]); sr_[i].vs1 = ld8(&Vh[(long)((k0) + 32 + sr) * LDK + sc]); \
;     sr_[i].ks0 = ld8(&Kh[(long)((k0) + sr) * LDK + sc]); sr_[i].ks1 = ld8(&Kh[(long)((k0) + 32 + sr) * LDK + sc]); } while (0)
; #define SWAIT() asm volatile("s_waitcnt vmcnt(4)" ::: "memory")
; #define SWRITE_I(B, i) do { LDSV(wv0 + (B) * 16384) = sr_[i].vs0; LDSV(wv1 + (B) * 16384) = sr_[i].vs1; LDSV(wk0 + (B) * 16384) = sr_[i].ks0; LDSV(wk1 + (B) * 16384) = sr_[i].ks1; } while (0)
; #define NOP_() do { } while (0)
; template <bool PARTIAL, bool FIXED> ...
;     ...
;   int j = 1;
;   for (; j + 6 < NT; j += 6) {
;     HALF_B(1, 0, SLOAD(1, (j + 2) * KVBLK), do { SWAIT(); SWRITE_I(2, 0); } while (0));
;     HALF_A(2, 1, NOP_(), SLOAD(0, (j + 3) * KVBLK), do { SWAIT(); SWRITE_I(0, 1); } while (0));
;     HALF_B(0, 2, SLOAD(1, (j + 4) * KVBLK), do { SWAIT(); SWRITE_I(1, 0); } while (0));
;     HALF_A(1, 0, NOP_(), SLOAD(0, (j + 5) * KVBLK), do { SWAIT(); SWRITE_I(2, 1); } while (0));
;     HALF_B(2, 1, SLOAD(1, (j + 6) * KVBLK), do { SWAIT(); SWRITE_I(0, 0); } while (0));
;     HALF_A(0, 2, NOP_(), SLOAD(0, (j + 7) * KVBLK), do { SWAIT(); SWRITE_I(1, 1); } while (0));
;   }
	v_mfma_f32_32x32x16_bf16 v[96:111], v[146:149], v[124:127], v[96:111]
	v_add_f32_e32 v215, v128, v80
	v_cvt_pk_bf16_f32 v80, v180, v181
	v_cvt_pk_bf16_f32 v81, v182, v183
	v_cvt_pk_bf16_f32 v82, v184, v185
	v_cvt_pk_bf16_f32 v83, v186, v187
	s_waitcnt lgkmcnt(0)
	v_mfma_f32_32x32x16_bf16 v[64:79], v[150:153], v[124:127], v[64:79]
	ds_read_b128 v[146:149], v192 offset:0
	ds_read_b128 v[150:153], v192 offset:8192
	v_cvt_pk_bf16_f32 v84, v188, v189
	v_cvt_pk_bf16_f32 v85, v196, v197
	v_cvt_pk_bf16_f32 v86, v198, v199
	v_cvt_pk_bf16_f32 v87, v216, v217
	v_cvt_pk_bf16_f32 v88, v236, v237
	v_cvt_pk_bf16_f32 v89, v238, v239
	s_waitcnt lgkmcnt(1)
	v_mfma_f32_32x32x16_bf16 v[96:111], v[146:149], v[130:133], v[96:111]
	v_cvt_pk_bf16_f32 v90, v247, v248
	v_cvt_pk_bf16_f32 v91, v249, v252
	v_cvt_pk_bf16_f32 v92, v200, v201
	v_cvt_pk_bf16_f32 v93, v202, v203
	v_cvt_pk_bf16_f32 v94, v204, v205
	s_waitcnt lgkmcnt(0)
	v_mfma_f32_32x32x16_bf16 v[64:79], v[150:153], v[130:133], v[64:79]
	ds_read_b128 v[146:149], v193 offset:0
	ds_read_b128 v[150:153], v193 offset:8192
	ds_read_b64_tr_b16 v[180:181], v206 offset:0x8000
	ds_read_b64_tr_b16 v[182:183], v206 offset:0x8800
	ds_read_b64_tr_b16 v[184:185], v206 offset:0x9000
	ds_read_b64_tr_b16 v[186:187], v206 offset:0x9800
	ds_read_b64_tr_b16 v[216:217], v206 offset:0xa000
	ds_read_b64_tr_b16 v[218:219], v206 offset:0xa800
	ds_read_b64_tr_b16 v[220:221], v206 offset:0xb000
	ds_read_b64_tr_b16 v[222:223], v206 offset:0xb800
	v_cvt_pk_bf16_f32 v95, v240, v241
	s_nop 0
	v_permlane32_swap_b32_e32 v80, v82
	v_permlane32_swap_b32_e32 v81, v83
	v_permlane32_swap_b32_e32 v84, v86
	v_permlane32_swap_b32_e32 v85, v87
	s_waitcnt lgkmcnt(9)
	v_mfma_f32_32x32x16_bf16 v[96:111], v[146:149], v[134:137], v[96:111]
	v_permlane32_swap_b32_e32 v88, v90
	v_permlane32_swap_b32_e32 v89, v91
	v_permlane32_swap_b32_e32 v92, v94
	v_permlane32_swap_b32_e32 v93, v95
	s_waitcnt lgkmcnt(8)
	v_mfma_f32_32x32x16_bf16 v[64:79], v[150:153], v[134:137], v[64:79]
	s_waitcnt vmcnt(0)
	ds_write_b128 v211, v[162:165] offset:16384
	s_nop 0
	s_waitcnt lgkmcnt(7)
	v_mfma_f32_32x32x16_bf16 v[0:15], v[80:83], v[180:183], v[0:15]
	ds_read_b64_tr_b16 v[180:181], v206 offset:0x8200
	ds_read_b64_tr_b16 v[182:183], v206 offset:0x8a00
	v_add_co_u32_e32 v150, vcc, s58, v178
	s_nop 1
	v_addc_co_u32_e32 v151, vcc, -1, v179, vcc
	s_waitcnt lgkmcnt(7)
	v_mfma_f32_32x32x16_bf16 v[0:15], v[84:87], v[184:187], v[0:15]
	ds_read_b64_tr_b16 v[184:185], v206 offset:0x9200
	ds_read_b64_tr_b16 v[186:187], v206 offset:0x9a00
	global_load_dwordx4 v[146:149], v[150:151], off
	global_load_dwordx4 v[154:157], v[150:151], off offset:-512
	s_nop 0
	global_load_dwordx4 v[150:153], v[178:179], off
	global_load_dwordx4 v[158:161], v[178:179], off offset:-512
	s_waitcnt lgkmcnt(7)
	v_mfma_f32_32x32x16_bf16 v[0:15], v[88:91], v[216:219], v[0:15]
	ds_read_b64_tr_b16 v[216:217], v206 offset:0xa200
	ds_read_b64_tr_b16 v[218:219], v206 offset:0xaa00
	s_waitcnt lgkmcnt(7)
	v_mfma_f32_32x32x16_bf16 v[0:15], v[92:95], v[220:223], v[0:15]
	ds_read_b64_tr_b16 v[220:221], v206 offset:0xb200
	ds_read_b64_tr_b16 v[222:223], v206 offset:0xba00
	ds_write_b128 v212, v[174:177] offset:16384
	s_waitcnt lgkmcnt(7)
	v_mfma_f32_32x32x16_bf16 v[16:31], v[80:83], v[180:183], v[16:31]
	ds_read_b64_tr_b16 v[180:181], v206 offset:0x8400
	ds_read_b64_tr_b16 v[182:183], v206 offset:0x8c00
	s_waitcnt lgkmcnt(7)
	v_mfma_f32_32x32x16_bf16 v[16:31], v[84:87], v[184:187], v[16:31]
	ds_read_b64_tr_b16 v[184:185], v206 offset:0x9400
	ds_read_b64_tr_b16 v[186:187], v206 offset:0x9c00
	s_waitcnt lgkmcnt(7)
	v_mfma_f32_32x32x16_bf16 v[16:31], v[88:91], v[216:219], v[16:31]
	ds_read_b64_tr_b16 v[216:217], v206 offset:0xa400
	ds_read_b64_tr_b16 v[218:219], v206 offset:0xac00
	s_waitcnt lgkmcnt(7)
	v_mfma_f32_32x32x16_bf16 v[16:31], v[92:95], v[220:223], v[16:31]
	ds_read_b64_tr_b16 v[220:221], v206 offset:0xb400
	ds_read_b64_tr_b16 v[222:223], v206 offset:0xbc00
	ds_write_b128 v213, v[166:169] offset:16384
	s_waitcnt lgkmcnt(7)
	v_mfma_f32_32x32x16_bf16 v[32:47], v[80:83], v[180:183], v[32:47]
	ds_read_b64_tr_b16 v[180:181], v206 offset:0x8600
	ds_read_b64_tr_b16 v[182:183], v206 offset:0x8e00
	v_exp_f32_e32 v229, v96
	v_exp_f32_e32 v243, v97
	s_waitcnt lgkmcnt(7)
	v_mfma_f32_32x32x16_bf16 v[32:47], v[84:87], v[184:187], v[32:47]
	ds_read_b64_tr_b16 v[184:185], v206 offset:0x9600
	ds_read_b64_tr_b16 v[186:187], v206 offset:0x9e00
	v_exp_f32_e32 v244, v98
	v_exp_f32_e32 v246, v99
	s_waitcnt lgkmcnt(7)
	v_mfma_f32_32x32x16_bf16 v[32:47], v[88:91], v[216:219], v[32:47]
	ds_read_b64_tr_b16 v[216:217], v206 offset:0xa600
	ds_read_b64_tr_b16 v[218:219], v206 offset:0xae00
	v_exp_f32_e32 v242, v100
	v_exp_f32_e32 v245, v101
	s_waitcnt lgkmcnt(7)
	v_mfma_f32_32x32x16_bf16 v[32:47], v[92:95], v[220:223], v[32:47]
	ds_read_b64_tr_b16 v[220:221], v206 offset:0xb600
	ds_read_b64_tr_b16 v[222:223], v206 offset:0xbe00
	v_exp_f32_e32 v227, v102
	v_exp_f32_e32 v228, v103
	ds_write_b128 v214, v[170:173] offset:16384
	s_waitcnt lgkmcnt(7)
	v_mfma_f32_32x32x16_bf16 v[48:63], v[80:83], v[180:183], v[48:63]
	s_waitcnt lgkmcnt(5)
	v_mfma_f32_32x32x16_bf16 v[48:63], v[84:87], v[184:187], v[48:63]
	v_exp_f32_e32 v226, v105
	v_exp_f32_e32 v224, v106
	v_exp_f32_e32 v225, v107
	s_waitcnt vmcnt(4)
	s_add_i32 s28, s28, 6
	v_lshl_add_u64 v[178:179], v[178:179], 0, s[60:61]
	s_waitcnt lgkmcnt(3)
	v_mfma_f32_32x32x16_bf16 v[48:63], v[88:91], v[216:219], v[48:63]
	v_exp_f32_e32 v219, v110
	s_cmpk_lt_u32 s28, 0x75
	s_waitcnt lgkmcnt(1)
	v_mfma_f32_32x32x16_bf16 v[48:63], v[92:95], v[220:223], v[48:63]
	v_exp_f32_e32 v223, v104
	v_exp_f32_e32 v220, v108
	v_exp_f32_e32 v222, v109
	v_exp_f32_e32 v221, v111
	s_cbranch_scc1 .LBB0_352
; __device__ __forceinline__ void finishSM(f32x16& p0, f32x16& p1, float alpha, float& l_reg, bf16x8& pa0, bf16x8& pa1, bf16x8& pa2, bf16x8& pa3) {
;   for (int r = 0; r < 16; ++r) p1[r] = __builtin_amdgcn_exp2f(p1[r]);
;   float ps = 0; for (int r = 0; r < 16; ++r) ps += p0[r]; for (int r = 0; r < 16; ++r) ps += p1[r];
;   { auto rr = __builtin_amdgcn_permlane32_swap(__float_as_uint(ps), __float_as_uint(ps), false, false);
;     ps = __uint_as_float(rr[0]) + __uint_as_float(rr[1]); }
;   l_reg = l_reg * alpha + ps;
;     ...
;   PK4(p0, 0, pa0); PK4(p0, 8, pa1); PK4(p1, 0, pa2); PK4(p1, 8, pa3);
;     ...
; }
	v_mov_b64_e32 v[200:201], 0x1600
	v_mov_b64_e32 v[202:203], 0x420
	v_mov_b64_e32 v[204:205], 0x41f
	v_mov_b64_e32 v[240:241], 0x1615
	v_mov_b32_e32 v252, 0x7fc00000
	v_readlane_b32 s8, v255, 42
	v_readlane_b32 s9, v255, 43
	s_add_u32 s2, s8, s6
	s_addc_u32 s3, s9, s7
	s_lshl_b32 s4, s65, 1
	s_add_u32 s2, s2, s4
	s_addc_u32 s3, s3, 0
	v_ashrrev_i32_e32 v82, 1, v195
	v_mov_b64_e32 v[80:81], s[2:3]
	v_mad_i64_i32 v[80:81], s[2:3], v82, s17, v[80:81]
	v_lshlrev_b32_e32 v82, 7, v195
	v_and_b32_e32 v128, 0x80, v82
	v_lshl_add_u64 v[80:81], v[80:81], 0, v[128:129]
	s_add_u32 s4, s8, s64
	global_load_dword v216, v[80:81], off
	v_cmp_gt_i32_e32 vcc, s14, v195
	v_mov_b32_e32 v80, 0xa00
	v_mov_b32_e32 v81, 0x800
	s_addc_u32 s5, s9, s57
	v_cndmask_b32_e32 v80, v80, v81, vcc
	v_mov_b32_e32 v81, v129
	v_bfe_u32 v82, v195, 1, 7
	v_lshl_add_u64 v[80:81], s[4:5], 0, v[80:81]
	s_lshl_b32 s46, s56, 1
	v_mul_u32_u24_e32 v82, 0x600, v82
	v_lshl_add_u64 v[80:81], v[80:81], 0, s[46:47]
	v_lshlrev_b32_e32 v82, 1, v82
	v_mov_b32_e32 v83, v129
	v_lshl_add_u64 v[80:81], v[80:81], 0, v[82:83]
	v_lshl_add_u64 v[80:81], v[80:81], 0, v[128:129]
	global_load_dword v217, v[80:81], off
	v_and_b32_e32 v247, 0x3fffffc0, v195
	s_waitcnt lgkmcnt(0)
	s_barrier
	ds_read_b128 v[80:83], v207 offset:16384
	ds_read_b128 v[96:99], v207 offset:24576
	ds_read_b128 v[100:103], v208 offset:16384
	ds_read_b128 v[170:173], v208 offset:24576
	v_exp_f32_e32 v104, v68
	v_exp_f32_e32 v105, v69
	s_waitcnt lgkmcnt(3)
	v_mfma_f32_32x32x16_bf16 v[80:95], v[80:83], v[142:145], 0
	v_exp_f32_e32 v106, v70
	v_exp_f32_e32 v107, v71
	v_exp_f32_e32 v108, v72
	v_exp_f32_e32 v109, v73
	v_exp_f32_e32 v110, v74
	v_exp_f32_e32 v111, v75
	v_exp_f32_e32 v196, v76
	s_waitcnt lgkmcnt(1)
	v_mfma_f32_32x32x16_bf16 v[80:95], v[100:103], v[138:141], v[80:95]
	ds_read_b128 v[100:103], v209 offset:16384
	ds_read_b128 v[162:165], v209 offset:24576
	v_exp_f32_e32 v197, v77
	v_exp_f32_e32 v198, v78
	v_exp_f32_e32 v79, v79
	s_waitcnt lgkmcnt(1)
	v_mfma_f32_32x32x16_bf16 v[80:95], v[100:103], v[112:115], v[80:95]
	ds_read_b128 v[100:103], v210 offset:16384
	ds_read_b128 v[166:169], v210 offset:24576
	s_waitcnt lgkmcnt(1)
	v_mfma_f32_32x32x16_bf16 v[80:95], v[100:103], v[116:119], v[80:95]
	ds_read_b128 v[100:103], v190 offset:16384
	ds_read_b128 v[174:177], v190 offset:24576
	s_waitcnt lgkmcnt(1)
	v_mfma_f32_32x32x16_bf16 v[80:95], v[100:103], v[120:123], v[80:95]
	ds_read_b128 v[100:103], v191 offset:16384
	ds_read_b128 v[178:181], v191 offset:24576
	s_waitcnt lgkmcnt(1)
	v_mfma_f32_32x32x16_bf16 v[80:95], v[100:103], v[124:127], v[80:95]
	ds_read_b128 v[100:103], v192 offset:16384
	ds_read_b128 v[182:185], v192 offset:24576
	s_waitcnt lgkmcnt(1)
	v_mfma_f32_32x32x16_bf16 v[80:95], v[100:103], v[130:133], v[80:95]
	ds_read_b128 v[100:103], v193 offset:16384
	ds_read_b128 v[186:189], v193 offset:24576
	s_waitcnt lgkmcnt(1)
	v_mfma_f32_32x32x16_bf16 v[80:95], v[100:103], v[134:137], v[80:95]
	v_exp_f32_e32 v100, v64
	v_add_f32_e32 v64, 0, v229
	v_add_f32_e32 v64, v243, v64
	v_add_f32_e32 v64, v244, v64
	v_add_f32_e32 v64, v246, v64
	v_add_f32_e32 v64, v242, v64
	v_add_f32_e32 v64, v245, v64
	v_add_f32_e32 v64, v227, v64
	v_add_f32_e32 v64, v228, v64
	v_add_f32_e32 v64, v223, v64
	v_add_f32_e32 v64, v226, v64
	v_add_f32_e32 v64, v224, v64
	v_add_f32_e32 v64, v225, v64
	v_add_f32_e32 v64, v220, v64
	v_exp_f32_e32 v101, v65
	v_add_f32_e32 v64, v222, v64
	v_exp_f32_e32 v102, v66
	v_add_f32_e32 v64, v219, v64
	v_exp_f32_e32 v103, v67
	v_add_f32_e32 v64, v221, v64
	v_add_f32_e32 v64, v100, v64
	v_add_f32_e32 v64, v101, v64
	v_add_f32_e32 v64, v102, v64
	v_add_f32_e32 v64, v103, v64
	v_add_f32_e32 v64, v104, v64
	v_add_f32_e32 v64, v105, v64
	v_add_f32_e32 v64, v106, v64
	v_add_f32_e32 v64, v107, v64
	v_add_f32_e32 v64, v108, v64
	v_add_f32_e32 v64, v109, v64
	v_add_f32_e32 v64, v110, v64
	v_add_f32_e32 v64, v111, v64
	v_add_f32_e32 v64, v196, v64
	v_add_f32_e32 v64, v197, v64
	v_add_f32_e32 v64, v198, v64
	v_add_f32_e32 v128, v79, v64
	v_mov_b32_e32 v218, v128
	s_nop 1
	v_permlane32_swap_b32_e32 v128, v218
	v_cvt_pk_bf16_f32 v64, v229, v243
	v_cvt_pk_bf16_f32 v65, v244, v246
	v_cvt_pk_bf16_f32 v66, v242, v245
	v_cvt_pk_bf16_f32 v67, v227, v228
	v_cvt_pk_bf16_f32 v68, v223, v226
	v_cvt_pk_bf16_f32 v69, v224, v225
	v_cvt_pk_bf16_f32 v70, v220, v222
	v_cvt_pk_bf16_f32 v71, v219, v221
	v_cvt_pk_bf16_f32 v72, v100, v101
	v_cvt_pk_bf16_f32 v73, v102, v103
	v_cvt_pk_bf16_f32 v74, v104, v105
	v_cvt_pk_bf16_f32 v75, v106, v107
	v_cvt_pk_bf16_f32 v76, v108, v109
	v_cvt_pk_bf16_f32 v77, v110, v111
	v_cvt_pk_bf16_f32 v78, v196, v197
	v_cvt_pk_bf16_f32 v79, v198, v79
	s_nop 0
	v_permlane32_swap_b32_e32 v64, v66
	v_permlane32_swap_b32_e32 v65, v67
	v_permlane32_swap_b32_e32 v68, v70
	v_permlane32_swap_b32_e32 v69, v71
	v_permlane32_swap_b32_e32 v72, v74
	v_permlane32_swap_b32_e32 v73, v75
	v_permlane32_swap_b32_e32 v76, v78
	v_permlane32_swap_b32_e32 v77, v79
	ds_read_b64_tr_b16 v[100:101], v206 offset:0
	ds_read_b64_tr_b16 v[102:103], v206 offset:0x800
	ds_read_b64_tr_b16 v[104:105], v206 offset:0x1000
	ds_read_b64_tr_b16 v[106:107], v206 offset:0x1800
	ds_read_b64_tr_b16 v[108:109], v206 offset:0x2000
	ds_read_b64_tr_b16 v[110:111], v206 offset:0x2800
	ds_read_b64_tr_b16 v[220:221], v206 offset:0x3000
	ds_read_b64_tr_b16 v[222:223], v206 offset:0x3800
	s_waitcnt lgkmcnt(0)
; #define SWRITE_I(B, i) do { LDSV(wv0 + (B) * 16384) = sr_[i].vs0; LDSV(wv1 + (B) * 16384) = sr_[i].vs1; LDSV(wk0 + (B) * 16384) = sr_[i].ks0; LDSV(wk1 + (B) * 16384) = sr_[i].ks1; } while (0)
; #define NOP_() do { } while (0)
; template <bool PARTIAL, bool FIXED> ...
;     ...
;   HALF_B(1, 0, NOP_(), SWRITE_I(2, 0));
;   HALF_A(2, 1, do { if (mask_last) { asm volatile("; masked tail tile" ::: "memory"); const float NEG = -INFINITY; \
;       _Pragma("unroll") for (int r = 8; r < 16; ++r) pA0[r] = NEG; _Pragma("unroll") for (int r = 0; r < 16; ++r) pA1[r] = NEG; } } while (0), NOP_(), NOP_());
	s_nop 0
	v_mfma_f32_32x32x16_bf16 v[0:15], v[64:67], v[100:103], v[0:15]
	ds_read_b64_tr_b16 v[100:101], v206 offset:0x200
	ds_read_b64_tr_b16 v[102:103], v206 offset:0xa00
	v_mfma_f32_32x32x16_bf16 v[0:15], v[68:71], v[104:107], v[0:15]
	ds_read_b64_tr_b16 v[104:105], v206 offset:0x1200
	ds_read_b64_tr_b16 v[106:107], v206 offset:0x1a00
	v_mfma_f32_32x32x16_bf16 v[0:15], v[72:75], v[108:111], v[0:15]
	ds_read_b64_tr_b16 v[108:109], v206 offset:0x2200
	ds_read_b64_tr_b16 v[110:111], v206 offset:0x2a00
	v_mfma_f32_32x32x16_bf16 v[0:15], v[76:79], v[220:223], v[0:15]
	ds_read_b64_tr_b16 v[220:221], v206 offset:0x3200
	ds_read_b64_tr_b16 v[222:223], v206 offset:0x3a00
	s_waitcnt lgkmcnt(0)
	v_mfma_f32_32x32x16_bf16 v[16:31], v[64:67], v[100:103], v[16:31]
	ds_read_b64_tr_b16 v[100:101], v206 offset:0x400
	ds_read_b64_tr_b16 v[102:103], v206 offset:0xc00
	v_mfma_f32_32x32x16_bf16 v[16:31], v[68:71], v[104:107], v[16:31]
	ds_read_b64_tr_b16 v[104:105], v206 offset:0x1400
	ds_read_b64_tr_b16 v[106:107], v206 offset:0x1c00
	v_mfma_f32_32x32x16_bf16 v[16:31], v[72:75], v[108:111], v[16:31]
	ds_read_b64_tr_b16 v[108:109], v206 offset:0x2400
	ds_read_b64_tr_b16 v[110:111], v206 offset:0x2c00
	v_mfma_f32_32x32x16_bf16 v[16:31], v[76:79], v[220:223], v[16:31]
	ds_read_b64_tr_b16 v[220:221], v206 offset:0x3400
	ds_read_b64_tr_b16 v[222:223], v206 offset:0x3c00
	s_waitcnt lgkmcnt(0)
	v_mfma_f32_32x32x16_bf16 v[32:47], v[64:67], v[100:103], v[32:47]
	ds_read_b64_tr_b16 v[100:101], v206 offset:0x600
	ds_read_b64_tr_b16 v[102:103], v206 offset:0xe00
	v_mfma_f32_32x32x16_bf16 v[32:47], v[68:71], v[104:107], v[32:47]
	ds_read_b64_tr_b16 v[104:105], v206 offset:0x1600
	ds_read_b64_tr_b16 v[106:107], v206 offset:0x1e00
	v_mfma_f32_32x32x16_bf16 v[32:47], v[72:75], v[108:111], v[32:47]
	ds_read_b64_tr_b16 v[108:109], v206 offset:0x2600
	ds_read_b64_tr_b16 v[110:111], v206 offset:0x2e00
	v_mfma_f32_32x32x16_bf16 v[32:47], v[76:79], v[220:223], v[32:47]
	ds_read_b64_tr_b16 v[220:221], v206 offset:0x3600
	ds_read_b64_tr_b16 v[222:223], v206 offset:0x3e00
	s_waitcnt lgkmcnt(0)
	v_mfma_f32_32x32x16_bf16 v[48:63], v[64:67], v[100:103], v[48:63]
	s_waitcnt vmcnt(5)
	ds_write_b128 v211, v[146:149] offset:32768
	s_waitcnt vmcnt(3)
	ds_write_b128 v212, v[150:153] offset:32768
	ds_write_b128 v213, v[154:157] offset:32768
	s_waitcnt vmcnt(2)
	ds_write_b128 v214, v[158:161] offset:32768
	s_waitcnt lgkmcnt(0)
	s_barrier
	v_mfma_f32_32x32x16_bf16 v[48:63], v[68:71], v[104:107], v[48:63]
	v_mfma_f32_32x32x16_bf16 v[48:63], v[72:75], v[108:111], v[48:63]
	v_mfma_f32_32x32x16_bf16 v[48:63], v[76:79], v[220:223], v[48:63]
	ds_read_b128 v[64:67], v207 offset:32768
	ds_read_b128 v[100:103], v208 offset:32768
	s_add_i32 s2, 0, 0x18000
	s_waitcnt lgkmcnt(1)
	v_mfma_f32_32x32x16_bf16 v[64:79], v[64:67], v[142:145], 0
	s_waitcnt lgkmcnt(0)
	v_mfma_f32_32x32x16_bf16 v[64:79], v[100:103], v[138:141], v[64:79]
	ds_read_b128 v[100:103], v209 offset:32768
	s_waitcnt lgkmcnt(0)
	v_mfma_f32_32x32x16_bf16 v[64:79], v[100:103], v[112:115], v[64:79]
	ds_read_b128 v[100:103], v210 offset:32768
	s_waitcnt lgkmcnt(0)
	v_mfma_f32_32x32x16_bf16 v[64:79], v[100:103], v[116:119], v[64:79]
	ds_read_b128 v[100:103], v190 offset:32768
	s_waitcnt lgkmcnt(0)
	v_mfma_f32_32x32x16_bf16 v[64:79], v[100:103], v[120:123], v[64:79]
	ds_read_b128 v[100:103], v191 offset:32768
	s_waitcnt lgkmcnt(0)
	v_mfma_f32_32x32x16_bf16 v[64:79], v[100:103], v[124:127], v[64:79]
	ds_read_b128 v[100:103], v192 offset:32768
	s_waitcnt lgkmcnt(0)
	v_mfma_f32_32x32x16_bf16 v[64:79], v[100:103], v[130:133], v[64:79]
	ds_read_b128 v[100:103], v193 offset:32768
	s_waitcnt lgkmcnt(0)
	v_and_b32_e32 v190, 63, v195
	v_lshlrev_b32_e32 v191, 4, v195
	v_and_b32_e32 v192, 31, v195
	v_bfe_u32 v193, v195, 5, 1
	v_mfma_f32_32x32x16_bf16 v[64:79], v[100:103], v[134:137], v[64:79]
	v_mfma_f32_32x32x16_bf16 v[96:111], v[96:99], v[142:145], 0
	s_nop 10
	v_exp_f32_e32 v72, v80
	v_exp_f32_e32 v80, v81
	v_exp_f32_e32 v73, v82
	v_exp_f32_e32 v81, v83
	v_exp_f32_e32 v74, v84
	v_add_f32_e32 v84, 0, v72
	v_exp_f32_e32 v82, v85
	v_mfma_f32_32x32x16_bf16 v[96:111], v[170:173], v[138:141], v[96:111]
	v_add_f32_e32 v84, v80, v84
	v_exp_f32_e32 v75, v86
	v_add_f32_e32 v84, v73, v84
	v_exp_f32_e32 v83, v87
	v_add_f32_e32 v84, v81, v84
	v_exp_f32_e32 v76, v88
	v_add_f32_e32 v84, v74, v84
	v_mfma_f32_32x32x16_bf16 v[96:111], v[162:165], v[112:115], v[96:111]
	v_exp_f32_e32 v85, v89
	v_add_f32_e32 v84, v82, v84
	v_exp_f32_e32 v77, v90
	v_add_f32_e32 v84, v75, v84
	v_exp_f32_e32 v87, v91
	v_add_f32_e32 v84, v83, v84
	v_exp_f32_e32 v78, v92
	v_mfma_f32_32x32x16_bf16 v[96:111], v[166:169], v[116:119], v[96:111]
	v_add_f32_e32 v84, v76, v84
	v_exp_f32_e32 v89, v93
	v_add_f32_e32 v84, v85, v84
	v_exp_f32_e32 v79, v94
	v_add_f32_e32 v84, v77, v84
	v_exp_f32_e32 v90, v95
	v_add_f32_e32 v84, v87, v84
	v_mfma_f32_32x32x16_bf16 v[96:111], v[174:177], v[120:123], v[96:111]
	v_add_f32_e32 v84, v78, v84
	v_add_f32_e32 v84, v89, v84
	v_add_f32_e32 v84, v79, v84
	v_add_f32_e32 v84, v90, v84
	v_lshl_add_u32 v88, v247, 2, s2
	v_cvt_pk_bf16_f32 v72, v72, v80
	v_cvt_pk_bf16_f32 v73, v73, v81
	v_mfma_f32_32x32x16_bf16 v[96:111], v[178:181], v[124:127], v[96:111]
	v_cvt_pk_bf16_f32 v74, v74, v82
	v_cvt_pk_bf16_f32 v75, v75, v83
	v_cvt_pk_bf16_f32 v76, v76, v85
	v_cvt_pk_bf16_f32 v77, v77, v87
	v_cvt_pk_bf16_f32 v78, v78, v89
	v_cvt_pk_bf16_f32 v79, v79, v90
	s_nop 0
	v_permlane32_swap_b32_e32 v72, v74
	v_mfma_f32_32x32x16_bf16 v[96:111], v[182:185], v[130:133], v[96:111]
	v_permlane32_swap_b32_e32 v73, v75
	v_permlane32_swap_b32_e32 v76, v78
	v_permlane32_swap_b32_e32 v77, v79
; #define SBAR() __builtin_amdgcn_sched_barrier(0)
; __device__ __forceinline__ void finishSM(f32x16& p0, f32x16& p1, float alpha, float& l_reg, bf16x8& pa0, bf16x8& pa1, bf16x8& pa2, bf16x8& pa3) {
;   for (int r = 0; r < 16; ++r) p1[r] = __builtin_amdgcn_exp2f(p1[r]);
;   float ps = 0; for (int r = 0; r < 16; ++r) ps += p0[r]; for (int r = 0; r < 16; ++r) ps += p1[r];
;   { auto rr = __builtin_amdgcn_permlane32_swap(__float_as_uint(ps), __float_as_uint(ps), false, false);
;     ps = __uint_as_float(rr[0]) + __uint_as_float(rr[1]); }
;   l_reg = l_reg * alpha + ps;
;     ...
;   PK4(p0, 0, pa0); PK4(p0, 8, pa1); PK4(p1, 0, pa2); PK4(p1, 8, pa3);
;     ...
; }
; template <int D0, int BOFF> __device__ __forceinline__ void pv_one_i(f32x16& od, int vb, bf16x8 pa0, bf16x8 pa1, bf16x8 pa2, bf16x8 pa3) {
;   const s16x4 l0 = tr_read<BOFF + v_rd_off(D0, 0, 0)>(vb), h0 = tr_read<BOFF + v_rd_off(D0, 0, 1)>(vb), l1 = tr_read<BOFF + v_rd_off(D0, 1, 0)>(vb), h1 = tr_read<BOFF + v_rd_off(D0, 1, 1)>(vb);
;   const s16x4 l2 = tr_read<BOFF + v_rd_off(D0, 2, 0)>(vb), h2 = tr_read<BOFF + v_rd_off(D0, 2, 1)>(vb), l3 = tr_read<BOFF + v_rd_off(D0, 3, 0)>(vb), h3 = tr_read<BOFF + v_rd_off(D0, 3, 1)>(vb);
;   asm volatile("s_waitcnt lgkmcnt(0)" ::: "memory"); SBAR();
;     ...
;   od = __builtin_amdgcn_mfma_f32_32x32x16_bf16(pa0, PK(l0, h0), od, 0, 0, 0);
;   od = __builtin_amdgcn_mfma_f32_32x32x16_bf16(pa1, PK(l1, h1), od, 0, 0, 0);
;   od = __builtin_amdgcn_mfma_f32_32x32x16_bf16(pa2, PK(l2, h2), od, 0, 0, 0);
;   od = __builtin_amdgcn_mfma_f32_32x32x16_bf16(pa3, PK(l3, h3), od, 0, 0, 0);
;     ...
; }
; template <int BOFF> __device__ __forceinline__ void pv_i(f32x16* o, int vb, bf16x8 pa0, bf16x8 pa1, bf16x8 pa2, bf16x8 pa3) {
;   pv_one_i<0, BOFF>(o[0], vb, pa0, pa1, pa2, pa3); pv_one_i<1, BOFF>(o[1], vb, pa0, pa1, pa2, pa3); pv_one_i<2, BOFF>(o[2], vb, pa0, pa1, pa2, pa3); pv_one_i<3, BOFF>(o[3], vb, pa0, pa1, pa2, pa3);
; }
	v_mfma_f32_32x32x16_bf16 v[96:111], v[186:189], v[134:137], v[96:111]
	s_nop 11
	v_exp_f32_e32 v91, v96
	v_exp_f32_e32 v92, v97
	v_exp_f32_e32 v93, v98
	v_exp_f32_e32 v94, v99
	v_exp_f32_e32 v95, v100
	v_add_f32_e32 v84, v84, v91
	v_exp_f32_e32 v96, v101
	v_add_f32_e32 v84, v92, v84
	v_exp_f32_e32 v97, v102
	v_add_f32_e32 v84, v93, v84
	v_exp_f32_e32 v98, v103
	v_add_f32_e32 v84, v94, v84
	v_exp_f32_e32 v99, v104
	v_add_f32_e32 v84, v95, v84
	v_exp_f32_e32 v100, v105
	v_add_f32_e32 v84, v96, v84
	v_exp_f32_e32 v101, v106
	v_add_f32_e32 v84, v97, v84
	v_exp_f32_e32 v102, v107
	v_add_f32_e32 v84, v98, v84
	v_exp_f32_e32 v103, v108
	v_add_f32_e32 v84, v99, v84
	v_exp_f32_e32 v104, v109
	v_add_f32_e32 v84, v100, v84
	v_exp_f32_e32 v105, v110
	v_add_f32_e32 v84, v101, v84
	v_exp_f32_e32 v106, v111
	v_add_f32_e32 v84, v102, v84
	v_add_f32_e32 v84, v103, v84
	v_add_f32_e32 v84, v104, v84
	v_add_f32_e32 v84, v105, v84
	v_add_f32_e32 v84, v106, v84
	v_mov_b32_e32 v86, v84
	s_nop 1
	v_permlane32_swap_b32_e32 v84, v86
	v_cvt_pk_bf16_f32 v80, v91, v92
	v_cvt_pk_bf16_f32 v81, v93, v94
	v_cvt_pk_bf16_f32 v82, v95, v96
	v_cvt_pk_bf16_f32 v83, v97, v98
	v_cvt_pk_bf16_f32 v90, v99, v100
	v_cvt_pk_bf16_f32 v91, v101, v102
	v_cvt_pk_bf16_f32 v92, v103, v104
	v_cvt_pk_bf16_f32 v93, v105, v106
	s_nop 0
	v_permlane32_swap_b32_e32 v80, v82
	v_permlane32_swap_b32_e32 v81, v83
	v_permlane32_swap_b32_e32 v90, v92
	v_permlane32_swap_b32_e32 v91, v93
	ds_read_b64_tr_b16 v[94:95], v206 offset:0x4000
	ds_read_b64_tr_b16 v[96:97], v206 offset:0x4800
	ds_read_b64_tr_b16 v[98:99], v206 offset:0x5000
	ds_read_b64_tr_b16 v[100:101], v206 offset:0x5800
	ds_read_b64_tr_b16 v[102:103], v206 offset:0x6000
	ds_read_b64_tr_b16 v[104:105], v206 offset:0x6800
	ds_read_b64_tr_b16 v[106:107], v206 offset:0x7000
	ds_read_b64_tr_b16 v[108:109], v206 offset:0x7800
	s_waitcnt lgkmcnt(0)
	s_nop 0
	v_mfma_f32_32x32x16_bf16 v[0:15], v[72:75], v[94:97], v[0:15]
	ds_read_b64_tr_b16 v[94:95], v206 offset:0x4200
	ds_read_b64_tr_b16 v[96:97], v206 offset:0x4a00
	v_mfma_f32_32x32x16_bf16 v[0:15], v[76:79], v[98:101], v[0:15]
	ds_read_b64_tr_b16 v[98:99], v206 offset:0x5200
	ds_read_b64_tr_b16 v[100:101], v206 offset:0x5a00
	v_mfma_f32_32x32x16_bf16 v[0:15], v[80:83], v[102:105], v[0:15]
	ds_read_b64_tr_b16 v[102:103], v206 offset:0x6200
	ds_read_b64_tr_b16 v[104:105], v206 offset:0x6a00
	v_mfma_f32_32x32x16_bf16 v[0:15], v[90:93], v[106:109], v[0:15]
	ds_read_b64_tr_b16 v[106:107], v206 offset:0x7200
	ds_read_b64_tr_b16 v[108:109], v206 offset:0x7a00
	s_waitcnt lgkmcnt(0)
	v_mfma_f32_32x32x16_bf16 v[16:31], v[72:75], v[94:97], v[16:31]
	ds_read_b64_tr_b16 v[94:95], v206 offset:0x4400
	ds_read_b64_tr_b16 v[96:97], v206 offset:0x4c00
	v_mfma_f32_32x32x16_bf16 v[16:31], v[76:79], v[98:101], v[16:31]
	ds_read_b64_tr_b16 v[98:99], v206 offset:0x5400
	ds_read_b64_tr_b16 v[100:101], v206 offset:0x5c00
	v_mfma_f32_32x32x16_bf16 v[16:31], v[80:83], v[102:105], v[16:31]
	ds_read_b64_tr_b16 v[102:103], v206 offset:0x6400
	ds_read_b64_tr_b16 v[104:105], v206 offset:0x6c00
	v_mfma_f32_32x32x16_bf16 v[16:31], v[90:93], v[106:109], v[16:31]
	ds_read_b64_tr_b16 v[106:107], v206 offset:0x7400
	ds_read_b64_tr_b16 v[108:109], v206 offset:0x7c00
	s_waitcnt lgkmcnt(0)
	v_mfma_f32_32x32x16_bf16 v[32:47], v[72:75], v[94:97], v[32:47]
	ds_read_b64_tr_b16 v[94:95], v206 offset:0x4600
	ds_read_b64_tr_b16 v[96:97], v206 offset:0x4e00
	v_mfma_f32_32x32x16_bf16 v[32:47], v[76:79], v[98:101], v[32:47]
	ds_read_b64_tr_b16 v[98:99], v206 offset:0x5600
	ds_read_b64_tr_b16 v[100:101], v206 offset:0x5e00
	v_mfma_f32_32x32x16_bf16 v[32:47], v[80:83], v[102:105], v[32:47]
	ds_read_b64_tr_b16 v[102:103], v206 offset:0x6600
	ds_read_b64_tr_b16 v[104:105], v206 offset:0x6e00
	v_mfma_f32_32x32x16_bf16 v[32:47], v[90:93], v[106:109], v[32:47]
	ds_read_b64_tr_b16 v[106:107], v206 offset:0x7600
	ds_read_b64_tr_b16 v[108:109], v206 offset:0x7e00
	s_waitcnt lgkmcnt(0)
; #define SBAR() __builtin_amdgcn_sched_barrier(0)
; __device__ __forceinline__ int crow(int r, int hi) { return (r & 3) + 8 * (r >> 2) + 4 * hi; }
; #define NOP_() do { } while (0)
; template <bool PARTIAL, bool FIXED> ...
;     ...
;   HALF_A(2, 1, do { if (mask_last) { asm volatile("; masked tail tile" ::: "memory"); const float NEG = -INFINITY; \
;       _Pragma("unroll") for (int r = 8; r < 16; ++r) pA0[r] = NEG; _Pragma("unroll") for (int r = 0; r < 16; ++r) pA1[r] = NEG; } } while (0), NOP_(), NOP_());
;     ...
;   SBAR(); finishSM(pA0, pA1, alA, l_reg, pa0, pa1, pa2, pa3); SBAR();
;   pv_i<2 * 16384>(o, vbi, pa0, pa1, pa2, pa3);
;     ...
;   if (PARTIAL) {
;     if (wid < 2) { float* po = PO + (wid * QBLK) * 128;
; #pragma unroll
;       for (int r = 0; r < 16; ++r) { const int orow = crow(r, hi);
; #pragma unroll
;         for (int d0 = 0; d0 < 4; ++d0) po[orow * 128 + d0 * 32 + r32] = o[d0][r]; }
;       if (hi == 0) { PO[8192 + (wid * QBLK + r32) * 2] = m_reg; PO[8192 + (wid * QBLK + r32) * 2 + 1] = l_reg; } }
;     __syncthreads();
;     return;
;   }
;   if (hi == 0) li_l[r32] = l_reg; asm volatile("s_waitcnt lgkmcnt(0)" ::: "memory");
	v_mfma_f32_32x32x16_bf16 v[48:63], v[72:75], v[94:97], v[48:63]
	v_exp_f32_e32 v64, v64
	v_exp_f32_e32 v65, v65
	v_exp_f32_e32 v66, v66
	v_exp_f32_e32 v67, v67
	v_exp_f32_e32 v68, v68
	v_exp_f32_e32 v69, v69
	v_exp_f32_e32 v70, v70
	v_mfma_f32_32x32x16_bf16 v[48:63], v[76:79], v[98:101], v[48:63]
	v_exp_f32_e32 v71, v71
	v_mfma_f32_32x32x16_bf16 v[48:63], v[80:83], v[102:105], v[48:63]
	v_mfma_f32_32x32x16_bf16 v[48:63], v[90:93], v[106:109], v[48:63]
	v_add_f32_e32 v72, 0, v64
	v_add_f32_e32 v72, v65, v72
	v_add_f32_e32 v72, v66, v72
	v_add_f32_e32 v72, v67, v72
	v_add_f32_e32 v72, v68, v72
	v_add_f32_e32 v72, v69, v72
	v_add_f32_e32 v72, v70, v72
	v_add_f32_e32 v72, v71, v72
	v_add_f32_e32 v85, 0, v72
	v_mov_b32_e32 v87, v85
	s_nop 1
	v_permlane32_swap_b32_e32 v85, v87
	v_cvt_pk_bf16_f32 v64, v64, v65
	v_cvt_pk_bf16_f32 v65, v66, v67
	v_cvt_pk_bf16_f32 v66, v68, v69
	v_cvt_pk_bf16_f32 v67, v70, v71
	v_cvt_pk_bf16_f32 v68, v129, v129
	v_cvt_pk_bf16_f32 v69, v129, v129
	v_cvt_pk_bf16_f32 v70, v129, v129
	v_cvt_pk_bf16_f32 v71, v129, v129
	v_cvt_pk_bf16_f32 v72, v129, v129
	v_cvt_pk_bf16_f32 v73, v129, v129
	v_cvt_pk_bf16_f32 v74, v129, v129
	v_cvt_pk_bf16_f32 v75, v129, v129
	v_cvt_pk_bf16_f32 v76, v129, v129
	v_cvt_pk_bf16_f32 v77, v129, v129
	v_cvt_pk_bf16_f32 v78, v129, v129
	v_cvt_pk_bf16_f32 v79, v129, v129
	s_nop 0
	v_permlane32_swap_b32_e32 v64, v66
	v_permlane32_swap_b32_e32 v65, v67
	v_permlane32_swap_b32_e32 v68, v70
	v_permlane32_swap_b32_e32 v69, v71
	v_permlane32_swap_b32_e32 v72, v74
	v_permlane32_swap_b32_e32 v73, v75
	v_permlane32_swap_b32_e32 v76, v78
	v_permlane32_swap_b32_e32 v77, v79
	ds_read_b64_tr_b16 v[80:81], v206 offset:0x8000
	ds_read_b64_tr_b16 v[82:83], v206 offset:0x8800
	ds_read_b64_tr_b16 v[90:91], v206 offset:0x9000
	ds_read_b64_tr_b16 v[92:93], v206 offset:0x9800
	ds_read_b64_tr_b16 v[94:95], v206 offset:0xa000
	ds_read_b64_tr_b16 v[96:97], v206 offset:0xa800
	ds_read_b64_tr_b16 v[98:99], v206 offset:0xb000
	ds_read_b64_tr_b16 v[100:101], v206 offset:0xb800
	s_waitcnt lgkmcnt(0)
	s_nop 0
	v_mfma_f32_32x32x16_bf16 v[0:15], v[64:67], v[80:83], v[0:15]
	ds_read_b64_tr_b16 v[80:81], v206 offset:0x8200
	ds_read_b64_tr_b16 v[82:83], v206 offset:0x8a00
	v_mfma_f32_32x32x16_bf16 v[0:15], v[68:71], v[90:93], v[0:15]
	ds_read_b64_tr_b16 v[90:91], v206 offset:0x9200
	ds_read_b64_tr_b16 v[92:93], v206 offset:0x9a00
	v_mfma_f32_32x32x16_bf16 v[0:15], v[72:75], v[94:97], v[0:15]
	ds_read_b64_tr_b16 v[94:95], v206 offset:0xa200
	ds_read_b64_tr_b16 v[96:97], v206 offset:0xaa00
	v_mfma_f32_32x32x16_bf16 v[0:15], v[76:79], v[98:101], v[0:15]
	ds_read_b64_tr_b16 v[98:99], v206 offset:0xb200
	ds_read_b64_tr_b16 v[100:101], v206 offset:0xba00
	s_waitcnt lgkmcnt(0)
	v_mfma_f32_32x32x16_bf16 v[16:31], v[64:67], v[80:83], v[16:31]
	ds_read_b64_tr_b16 v[80:81], v206 offset:0x8400
	ds_read_b64_tr_b16 v[82:83], v206 offset:0x8c00
	v_mfma_f32_32x32x16_bf16 v[16:31], v[68:71], v[90:93], v[16:31]
	ds_read_b64_tr_b16 v[90:91], v206 offset:0x9400
	ds_read_b64_tr_b16 v[92:93], v206 offset:0x9c00
	v_mfma_f32_32x32x16_bf16 v[16:31], v[72:75], v[94:97], v[16:31]
	ds_read_b64_tr_b16 v[94:95], v206 offset:0xa400
	ds_read_b64_tr_b16 v[96:97], v206 offset:0xac00
	v_mfma_f32_32x32x16_bf16 v[16:31], v[76:79], v[98:101], v[16:31]
	ds_read_b64_tr_b16 v[98:99], v206 offset:0xb400
	ds_read_b64_tr_b16 v[100:101], v206 offset:0xbc00
	s_waitcnt lgkmcnt(0)
	v_mfma_f32_32x32x16_bf16 v[32:47], v[64:67], v[80:83], v[32:47]
	ds_read_b64_tr_b16 v[80:81], v206 offset:0x8600
	ds_read_b64_tr_b16 v[82:83], v206 offset:0x8e00
	v_mfma_f32_32x32x16_bf16 v[32:47], v[68:71], v[90:93], v[32:47]
	ds_read_b64_tr_b16 v[90:91], v206 offset:0x9600
	ds_read_b64_tr_b16 v[92:93], v206 offset:0x9e00
	v_mfma_f32_32x32x16_bf16 v[32:47], v[72:75], v[94:97], v[32:47]
	ds_read_b64_tr_b16 v[94:95], v206 offset:0xa600
	ds_read_b64_tr_b16 v[96:97], v206 offset:0xae00
	v_mfma_f32_32x32x16_bf16 v[32:47], v[76:79], v[98:101], v[32:47]
	ds_read_b64_tr_b16 v[98:99], v206 offset:0xb600
	ds_read_b64_tr_b16 v[100:101], v206 offset:0xbe00
	s_waitcnt lgkmcnt(0)
	v_mfma_f32_32x32x16_bf16 v[48:63], v[64:67], v[80:83], v[48:63]
	v_cmp_gt_u32_e32 vcc, 32, v190
	v_mfma_f32_32x32x16_bf16 v[48:63], v[68:71], v[90:93], v[48:63]
	v_mfma_f32_32x32x16_bf16 v[48:63], v[72:75], v[94:97], v[48:63]
	v_mfma_f32_32x32x16_bf16 v[48:63], v[76:79], v[98:101], v[48:63]
	s_and_saveexec_b64 s[28:29], vcc
	s_cbranch_execz .LBB0_309
	v_add_f32_e32 v64, v128, v218
	v_add_f32_e32 v66, v215, v64
	v_pk_add_f32 v[64:65], v[84:85], v[86:87]
	v_lshl_add_u32 v67, v192, 2, v88
	v_add_f32_e32 v64, v66, v64
	v_add_f32_e32 v64, v64, v65
	ds_write_b32 v67, v64
	s_branch .LBB0_309
